# v29 + M0 formed directly by s_add_i32 (17 temporaries + s_mov_b32 copies removed) in the K-loop load segments
# baseline (speedup 1.0000x reference)
.LBB0_134:
	s_add_u32 s0, s34, 0xfff00080
	s_addc_u32 s1, s35, -1
	s_cmp_eq_u32 s60, 60
	s_cselect_b32 s39, s12, s1
	s_cselect_b32 s38, s13, s0
	s_cselect_b32 s37, s15, s59
	s_cselect_b32 s36, s57, s58
	s_add_i32 m0, s29, 0xc000
	ds_read_b128 v[148:151], v156
	global_load_lds_dwordx4 v140, s[34:35]
	s_add_i32 m0, s29, 0xe000
	ds_read_b128 v[160:163], v156 offset:1024
	global_load_lds_dwordx4 v142, s[34:35]
	ds_read_b128 v[164:167], v156 offset:2048
	ds_read_b128 v[168:171], v156 offset:3072
	ds_read_b128 v[172:175], v157
	ds_read_b128 v[176:179], v157 offset:1024
	ds_read_b128 v[180:183], v157 offset:2048
	ds_read_b128 v[184:187], v157 offset:3072
	ds_read_b128 v[188:191], v158
	ds_read_b128 v[192:195], v158 offset:1024
	ds_read_b128 v[196:199], v158 offset:2048
	ds_read_b128 v[200:203], v158 offset:3072
	ds_read_b128 v[208:211], v158 offset:4096
	ds_read_b128 v[212:215], v158 offset:5120
	ds_read_b128 v[216:219], v158 offset:6144
	ds_read_b128 v[220:223], v158 offset:7168
	s_waitcnt vmcnt(8) lgkmcnt(0)
	s_setprio 3
	s_barrier
	v_mfma_f32_16x16x32_bf16 v[124:127], v[148:151], v[188:191], v[124:127]
	v_mfma_f32_16x16x32_bf16 v[120:123], v[164:167], v[188:191], v[120:123]
	v_mfma_f32_16x16x32_bf16 v[108:111], v[148:151], v[196:199], v[108:111]
	v_mfma_f32_16x16x32_bf16 v[104:107], v[164:167], v[196:199], v[104:107]
	v_mfma_f32_16x16x32_bf16 v[92:95], v[148:151], v[208:211], v[92:95]
	v_mfma_f32_16x16x32_bf16 v[88:91], v[164:167], v[208:211], v[88:91]
	v_mfma_f32_16x16x32_bf16 v[76:79], v[148:151], v[216:219], v[76:79]
	v_mfma_f32_16x16x32_bf16 v[72:75], v[164:167], v[216:219], v[72:75]
	v_mfma_f32_16x16x32_bf16 v[124:127], v[160:163], v[192:195], v[124:127]
	v_mfma_f32_16x16x32_bf16 v[120:123], v[168:171], v[192:195], v[120:123]
	v_mfma_f32_16x16x32_bf16 v[108:111], v[160:163], v[200:203], v[108:111]
	v_mfma_f32_16x16x32_bf16 v[104:107], v[168:171], v[200:203], v[104:107]
	v_mfma_f32_16x16x32_bf16 v[92:95], v[160:163], v[212:215], v[92:95]
	v_mfma_f32_16x16x32_bf16 v[88:91], v[168:171], v[212:215], v[88:91]
	v_mfma_f32_16x16x32_bf16 v[76:79], v[160:163], v[220:223], v[76:79]
	v_mfma_f32_16x16x32_bf16 v[72:75], v[168:171], v[220:223], v[72:75]
	v_mfma_f32_16x16x32_bf16 v[116:119], v[172:175], v[188:191], v[116:119]
	v_mfma_f32_16x16x32_bf16 v[112:115], v[180:183], v[188:191], v[112:115]
	v_mfma_f32_16x16x32_bf16 v[100:103], v[172:175], v[196:199], v[100:103]
	v_mfma_f32_16x16x32_bf16 v[96:99], v[180:183], v[196:199], v[96:99]
	v_mfma_f32_16x16x32_bf16 v[84:87], v[172:175], v[208:211], v[84:87]
	v_mfma_f32_16x16x32_bf16 v[80:83], v[180:183], v[208:211], v[80:83]
	v_mfma_f32_16x16x32_bf16 v[68:71], v[172:175], v[216:219], v[68:71]
	v_mfma_f32_16x16x32_bf16 v[64:67], v[180:183], v[216:219], v[64:67]
	v_mfma_f32_16x16x32_bf16 v[116:119], v[176:179], v[192:195], v[116:119]
	v_mfma_f32_16x16x32_bf16 v[112:115], v[184:187], v[192:195], v[112:115]
	v_mfma_f32_16x16x32_bf16 v[100:103], v[176:179], v[200:203], v[100:103]
	v_mfma_f32_16x16x32_bf16 v[96:99], v[184:187], v[200:203], v[96:99]
	v_mfma_f32_16x16x32_bf16 v[84:87], v[176:179], v[212:215], v[84:87]
	v_mfma_f32_16x16x32_bf16 v[80:83], v[184:187], v[212:215], v[80:83]
	v_mfma_f32_16x16x32_bf16 v[68:71], v[176:179], v[220:223], v[68:71]
	v_mfma_f32_16x16x32_bf16 v[64:67], v[184:187], v[220:223], v[64:67]
	s_barrier
	s_setprio 0
	s_add_i32 m0, s51, s41
	ds_read_b128 v[188:191], v158 offset:16384
	global_load_lds_dwordx4 v132, s[36:37]
	s_add_i32 m0, m0, 0x2000
	ds_read_b128 v[192:195], v158 offset:17408
	global_load_lds_dwordx4 v136, s[36:37]
	s_add_u32 s62, s36, 0x100000
	s_addc_u32 s63, s37, 0
	s_add_i32 m0, s52, s41
	ds_read_b128 v[196:199], v158 offset:18432
	global_load_lds_dwordx4 v132, s[62:63]
	s_add_i32 m0, m0, 0x2000
	ds_read_b128 v[200:203], v158 offset:19456
	global_load_lds_dwordx4 v136, s[62:63]
	s_mov_b32 m0, s29
	ds_read_b128 v[208:211], v158 offset:20480
	global_load_lds_dwordx4 v130, s[38:39]
	s_mov_b32 m0, s31
	ds_read_b128 v[212:215], v158 offset:21504
	global_load_lds_dwordx4 v134, s[38:39]
	ds_read_b128 v[216:219], v158 offset:22528
	ds_read_b128 v[220:223], v158 offset:23552
	s_waitcnt vmcnt(8) lgkmcnt(0)
	s_setprio 3
	s_barrier
	v_mfma_f32_16x16x32_bf16 v[60:63], v[148:151], v[188:191], v[60:63]
	v_mfma_f32_16x16x32_bf16 v[56:59], v[164:167], v[188:191], v[56:59]
	v_mfma_f32_16x16x32_bf16 v[44:47], v[148:151], v[196:199], v[44:47]
	v_mfma_f32_16x16x32_bf16 v[40:43], v[164:167], v[196:199], v[40:43]
	v_mfma_f32_16x16x32_bf16 v[28:31], v[148:151], v[208:211], v[28:31]
	v_mfma_f32_16x16x32_bf16 v[24:27], v[164:167], v[208:211], v[24:27]
	v_mfma_f32_16x16x32_bf16 v[12:15], v[148:151], v[216:219], v[12:15]
	v_mfma_f32_16x16x32_bf16 v[8:11], v[164:167], v[216:219], v[8:11]
	v_mfma_f32_16x16x32_bf16 v[60:63], v[160:163], v[192:195], v[60:63]
	v_mfma_f32_16x16x32_bf16 v[56:59], v[168:171], v[192:195], v[56:59]
	v_mfma_f32_16x16x32_bf16 v[44:47], v[160:163], v[200:203], v[44:47]
	v_mfma_f32_16x16x32_bf16 v[40:43], v[168:171], v[200:203], v[40:43]
	v_mfma_f32_16x16x32_bf16 v[28:31], v[160:163], v[212:215], v[28:31]
	v_mfma_f32_16x16x32_bf16 v[24:27], v[168:171], v[212:215], v[24:27]
	v_mfma_f32_16x16x32_bf16 v[12:15], v[160:163], v[220:223], v[12:15]
	v_mfma_f32_16x16x32_bf16 v[8:11], v[168:171], v[220:223], v[8:11]
	v_mfma_f32_16x16x32_bf16 v[52:55], v[172:175], v[188:191], v[52:55]
	v_mfma_f32_16x16x32_bf16 v[48:51], v[180:183], v[188:191], v[48:51]
	v_mfma_f32_16x16x32_bf16 v[36:39], v[172:175], v[196:199], v[36:39]
	v_mfma_f32_16x16x32_bf16 v[32:35], v[180:183], v[196:199], v[32:35]
	v_mfma_f32_16x16x32_bf16 v[20:23], v[172:175], v[208:211], v[20:23]
	v_mfma_f32_16x16x32_bf16 v[16:19], v[180:183], v[208:211], v[16:19]
	v_mfma_f32_16x16x32_bf16 v[4:7], v[172:175], v[216:219], v[4:7]
	v_mfma_f32_16x16x32_bf16 v[0:3], v[180:183], v[216:219], v[0:3]
	v_mfma_f32_16x16x32_bf16 v[52:55], v[176:179], v[192:195], v[52:55]
	v_mfma_f32_16x16x32_bf16 v[48:51], v[184:187], v[192:195], v[48:51]
	v_mfma_f32_16x16x32_bf16 v[36:39], v[176:179], v[200:203], v[36:39]
	v_mfma_f32_16x16x32_bf16 v[32:35], v[184:187], v[200:203], v[32:35]
	v_mfma_f32_16x16x32_bf16 v[20:23], v[176:179], v[212:215], v[20:23]
	v_mfma_f32_16x16x32_bf16 v[16:19], v[184:187], v[212:215], v[16:19]
	v_mfma_f32_16x16x32_bf16 v[4:7], v[176:179], v[220:223], v[4:7]
	v_mfma_f32_16x16x32_bf16 v[0:3], v[184:187], v[220:223], v[0:3]
	s_barrier
	s_setprio 0
	s_add_i32 s0, 0, 0x18000
	s_add_i32 s1, 0, 0x1c000
	ds_read_b128 v[148:151], v228
	ds_read_b128 v[160:163], v228 offset:1024
	ds_read_b128 v[164:167], v228 offset:2048
	ds_read_b128 v[168:171], v228 offset:3072
	ds_read_b128 v[172:175], v229
	ds_read_b128 v[176:179], v229 offset:1024
	ds_read_b128 v[180:183], v229 offset:2048
	ds_read_b128 v[184:187], v229 offset:3072
	s_add_u32 s38, s38, 0x100000
	s_addc_u32 s39, s39, 0
	s_mov_b32 m0, s42
	ds_read_b128 v[188:191], v158 offset:32768
	global_load_lds_dwordx4 v130, s[38:39]
	s_mov_b32 m0, s43
	ds_read_b128 v[192:195], v158 offset:33792
	global_load_lds_dwordx4 v134, s[38:39]
	ds_read_b128 v[196:199], v158 offset:34816
	ds_read_b128 v[200:203], v158 offset:35840
	ds_read_b128 v[208:211], v158 offset:36864
	ds_read_b128 v[212:215], v158 offset:37888
	ds_read_b128 v[216:219], v158 offset:38912
	ds_read_b128 v[220:223], v158 offset:39936
	s_waitcnt vmcnt(8) lgkmcnt(0)
	s_setprio 3
	s_barrier
	v_mfma_f32_16x16x32_bf16 v[124:127], v[148:151], v[188:191], v[124:127]
	v_mfma_f32_16x16x32_bf16 v[120:123], v[164:167], v[188:191], v[120:123]
	v_mfma_f32_16x16x32_bf16 v[108:111], v[148:151], v[196:199], v[108:111]
	v_mfma_f32_16x16x32_bf16 v[104:107], v[164:167], v[196:199], v[104:107]
	v_mfma_f32_16x16x32_bf16 v[92:95], v[148:151], v[208:211], v[92:95]
	v_mfma_f32_16x16x32_bf16 v[88:91], v[164:167], v[208:211], v[88:91]
	v_mfma_f32_16x16x32_bf16 v[76:79], v[148:151], v[216:219], v[76:79]
	v_mfma_f32_16x16x32_bf16 v[72:75], v[164:167], v[216:219], v[72:75]
	v_mfma_f32_16x16x32_bf16 v[124:127], v[160:163], v[192:195], v[124:127]
	v_mfma_f32_16x16x32_bf16 v[120:123], v[168:171], v[192:195], v[120:123]
	v_mfma_f32_16x16x32_bf16 v[108:111], v[160:163], v[200:203], v[108:111]
	v_mfma_f32_16x16x32_bf16 v[104:107], v[168:171], v[200:203], v[104:107]
	v_mfma_f32_16x16x32_bf16 v[92:95], v[160:163], v[212:215], v[92:95]
	v_mfma_f32_16x16x32_bf16 v[88:91], v[168:171], v[212:215], v[88:91]
	v_mfma_f32_16x16x32_bf16 v[76:79], v[160:163], v[220:223], v[76:79]
	v_mfma_f32_16x16x32_bf16 v[72:75], v[168:171], v[220:223], v[72:75]
	v_mfma_f32_16x16x32_bf16 v[116:119], v[172:175], v[188:191], v[116:119]
	v_mfma_f32_16x16x32_bf16 v[112:115], v[180:183], v[188:191], v[112:115]
	v_mfma_f32_16x16x32_bf16 v[100:103], v[172:175], v[196:199], v[100:103]
	v_mfma_f32_16x16x32_bf16 v[96:99], v[180:183], v[196:199], v[96:99]
	v_mfma_f32_16x16x32_bf16 v[84:87], v[172:175], v[208:211], v[84:87]
	v_mfma_f32_16x16x32_bf16 v[80:83], v[180:183], v[208:211], v[80:83]
	v_mfma_f32_16x16x32_bf16 v[68:71], v[172:175], v[216:219], v[68:71]
	v_mfma_f32_16x16x32_bf16 v[64:67], v[180:183], v[216:219], v[64:67]
	v_mfma_f32_16x16x32_bf16 v[116:119], v[176:179], v[192:195], v[116:119]
	v_mfma_f32_16x16x32_bf16 v[112:115], v[184:187], v[192:195], v[112:115]
	v_mfma_f32_16x16x32_bf16 v[100:103], v[176:179], v[200:203], v[100:103]
	v_mfma_f32_16x16x32_bf16 v[96:99], v[184:187], v[200:203], v[96:99]
	v_mfma_f32_16x16x32_bf16 v[84:87], v[176:179], v[212:215], v[84:87]
	v_mfma_f32_16x16x32_bf16 v[80:83], v[184:187], v[212:215], v[80:83]
	v_mfma_f32_16x16x32_bf16 v[68:71], v[176:179], v[220:223], v[68:71]
	v_mfma_f32_16x16x32_bf16 v[64:67], v[184:187], v[220:223], v[64:67]
	s_barrier
	s_setprio 0
	s_add_i32 s0, s0, s41
	s_add_u32 s100, s36, 0x80
	s_addc_u32 s101, s37, 0
	s_mov_b32 m0, s0
	ds_read_b128 v[188:191], v158 offset:49152
	global_load_lds_dwordx4 v132, s[100:101]
	s_add_i32 m0, s0, 0x2000
	ds_read_b128 v[192:195], v158 offset:50176
	global_load_lds_dwordx4 v136, s[100:101]
	s_add_u32 s36, s36, 0x100080
	s_addc_u32 s37, s37, 0
	s_add_i32 m0, s1, s41
	ds_read_b128 v[196:199], v158 offset:51200
	global_load_lds_dwordx4 v132, s[36:37]
	s_add_i32 m0, m0, 0x2000
	ds_read_b128 v[200:203], v158 offset:52224
	global_load_lds_dwordx4 v136, s[36:37]
	s_add_u32 s100, s38, 0xfff00080
	s_addc_u32 s101, s39, -1
	s_mov_b32 m0, s46
	ds_read_b128 v[208:211], v158 offset:53248
	global_load_lds_dwordx4 v130, s[100:101]
	s_mov_b32 m0, s47
	ds_read_b128 v[212:215], v158 offset:54272
	global_load_lds_dwordx4 v134, s[100:101]
	ds_read_b128 v[216:219], v158 offset:55296
	ds_read_b128 v[220:223], v158 offset:56320
	s_waitcnt vmcnt(8) lgkmcnt(0)
	s_setprio 3
	s_barrier
	v_mfma_f32_16x16x32_bf16 v[60:63], v[148:151], v[188:191], v[60:63]
	v_mfma_f32_16x16x32_bf16 v[56:59], v[164:167], v[188:191], v[56:59]
	v_mfma_f32_16x16x32_bf16 v[44:47], v[148:151], v[196:199], v[44:47]
	v_mfma_f32_16x16x32_bf16 v[40:43], v[164:167], v[196:199], v[40:43]
	v_mfma_f32_16x16x32_bf16 v[28:31], v[148:151], v[208:211], v[28:31]
	v_mfma_f32_16x16x32_bf16 v[24:27], v[164:167], v[208:211], v[24:27]
	v_mfma_f32_16x16x32_bf16 v[12:15], v[148:151], v[216:219], v[12:15]
	v_mfma_f32_16x16x32_bf16 v[8:11], v[164:167], v[216:219], v[8:11]
	v_mfma_f32_16x16x32_bf16 v[60:63], v[160:163], v[192:195], v[60:63]
	v_mfma_f32_16x16x32_bf16 v[56:59], v[168:171], v[192:195], v[56:59]
	v_mfma_f32_16x16x32_bf16 v[44:47], v[160:163], v[200:203], v[44:47]
	v_mfma_f32_16x16x32_bf16 v[40:43], v[168:171], v[200:203], v[40:43]
	v_mfma_f32_16x16x32_bf16 v[28:31], v[160:163], v[212:215], v[28:31]
	v_mfma_f32_16x16x32_bf16 v[24:27], v[168:171], v[212:215], v[24:27]
	v_mfma_f32_16x16x32_bf16 v[12:15], v[160:163], v[220:223], v[12:15]
	v_mfma_f32_16x16x32_bf16 v[8:11], v[168:171], v[220:223], v[8:11]
	v_mfma_f32_16x16x32_bf16 v[52:55], v[172:175], v[188:191], v[52:55]
	v_mfma_f32_16x16x32_bf16 v[48:51], v[180:183], v[188:191], v[48:51]
	v_mfma_f32_16x16x32_bf16 v[36:39], v[172:175], v[196:199], v[36:39]
	v_mfma_f32_16x16x32_bf16 v[32:35], v[180:183], v[196:199], v[32:35]
	v_mfma_f32_16x16x32_bf16 v[20:23], v[172:175], v[208:211], v[20:23]
	v_mfma_f32_16x16x32_bf16 v[16:19], v[180:183], v[208:211], v[16:19]
	v_mfma_f32_16x16x32_bf16 v[4:7], v[172:175], v[216:219], v[4:7]
	v_mfma_f32_16x16x32_bf16 v[0:3], v[180:183], v[216:219], v[0:3]
	v_mfma_f32_16x16x32_bf16 v[52:55], v[176:179], v[192:195], v[52:55]
	v_mfma_f32_16x16x32_bf16 v[48:51], v[184:187], v[192:195], v[48:51]
	v_mfma_f32_16x16x32_bf16 v[36:39], v[176:179], v[200:203], v[36:39]
	v_mfma_f32_16x16x32_bf16 v[32:35], v[184:187], v[200:203], v[32:35]
	v_mfma_f32_16x16x32_bf16 v[20:23], v[176:179], v[212:215], v[20:23]
	v_mfma_f32_16x16x32_bf16 v[16:19], v[184:187], v[212:215], v[16:19]
	v_mfma_f32_16x16x32_bf16 v[4:7], v[176:179], v[220:223], v[4:7]
	v_mfma_f32_16x16x32_bf16 v[0:3], v[184:187], v[220:223], v[0:3]
	s_barrier
	s_setprio 0
	s_add_u32 s34, s34, 0x100
	s_addc_u32 s35, s35, 0
	s_add_i32 s60, s60, 2
	s_add_u32 s58, s58, 0x100
	s_addc_u32 s59, s59, 0
	s_cmp_gt_u32 s60, 61
	s_cbranch_scc0 .LBB0_134
	s_and_b64 vcc, exec, s[10:11]
	s_cbranch_vccz .LBB0_137
	s_barrier

.LBB0_425:
	ds_read_b128 v[146:149], v214
	ds_read_b128 v[150:153], v214 offset:1024
	ds_read_b128 v[154:157], v214 offset:2048
	ds_read_b128 v[158:161], v214 offset:3072
	ds_read_b128 v[162:165], v215
	ds_read_b128 v[166:169], v215 offset:1024
	ds_read_b128 v[170:173], v215 offset:2048
	ds_read_b128 v[174:177], v215 offset:3072
	s_add_i32 s13, s13, 2
	s_lshr_b32 s0, s13, 6
	s_mul_hi_u32 s1, s0, 0x8200000
	s_mul_i32 s0, s0, 0x8200000
	s_add_u32 s0, s46, s0
	s_addc_u32 s1, s47, s1
	s_and_b32 s35, s35, 0x1f00
	s_add_u32 s0, s0, s35
	s_addc_u32 s1, s1, 0
	s_add_u32 s0, s0, 0x100080
	s_addc_u32 s1, s1, 0
	s_add_i32 m0, s43, 0xc000
	ds_read_b128 v[178:181], v145
	ds_read_b128 v[182:185], v145 offset:1024
	ds_read_b128 v[186:189], v145 offset:2048
	ds_read_b128 v[190:193], v145 offset:3072
	ds_read_b128 v[194:197], v145 offset:4096
	ds_read_b128 v[198:201], v145 offset:5120
	ds_read_b128 v[202:205], v145 offset:6144
	global_load_lds_dwordx4 v128, s[0:1]
	s_add_i32 m0, s43, 0xe000
	ds_read_b128 v[206:209], v145 offset:7168
	global_load_lds_dwordx4 v132, s[0:1]
	s_waitcnt vmcnt(8) lgkmcnt(0)
	s_setprio 3
	s_barrier
	v_mfma_f32_16x16x32_bf16 v[124:127], v[146:149], v[178:181], v[124:127]
	v_mfma_f32_16x16x32_bf16 v[120:123], v[154:157], v[178:181], v[120:123]
	v_mfma_f32_16x16x32_bf16 v[116:119], v[146:149], v[186:189], v[116:119]
	v_mfma_f32_16x16x32_bf16 v[108:111], v[154:157], v[186:189], v[108:111]
	v_mfma_f32_16x16x32_bf16 v[100:103], v[146:149], v[194:197], v[100:103]
	v_mfma_f32_16x16x32_bf16 v[92:95], v[154:157], v[194:197], v[92:95]
	v_mfma_f32_16x16x32_bf16 v[84:87], v[146:149], v[202:205], v[84:87]
	v_mfma_f32_16x16x32_bf16 v[76:79], v[154:157], v[202:205], v[76:79]
	v_mfma_f32_16x16x32_bf16 v[124:127], v[150:153], v[182:185], v[124:127]
	v_mfma_f32_16x16x32_bf16 v[120:123], v[158:161], v[182:185], v[120:123]
	v_mfma_f32_16x16x32_bf16 v[116:119], v[150:153], v[190:193], v[116:119]
	v_mfma_f32_16x16x32_bf16 v[108:111], v[158:161], v[190:193], v[108:111]
	v_mfma_f32_16x16x32_bf16 v[100:103], v[150:153], v[198:201], v[100:103]
	v_mfma_f32_16x16x32_bf16 v[92:95], v[158:161], v[198:201], v[92:95]
	v_mfma_f32_16x16x32_bf16 v[84:87], v[150:153], v[206:209], v[84:87]
	v_mfma_f32_16x16x32_bf16 v[76:79], v[158:161], v[206:209], v[76:79]
	v_mfma_f32_16x16x32_bf16 v[112:115], v[162:165], v[178:181], v[112:115]
	v_mfma_f32_16x16x32_bf16 v[104:107], v[170:173], v[178:181], v[104:107]
	v_mfma_f32_16x16x32_bf16 v[96:99], v[162:165], v[186:189], v[96:99]
	v_mfma_f32_16x16x32_bf16 v[88:91], v[170:173], v[186:189], v[88:91]
	v_mfma_f32_16x16x32_bf16 v[80:83], v[162:165], v[194:197], v[80:83]
	v_mfma_f32_16x16x32_bf16 v[72:75], v[170:173], v[194:197], v[72:75]
	v_mfma_f32_16x16x32_bf16 v[68:71], v[162:165], v[202:205], v[68:71]
	v_mfma_f32_16x16x32_bf16 v[64:67], v[170:173], v[202:205], v[64:67]
	v_mfma_f32_16x16x32_bf16 v[112:115], v[166:169], v[182:185], v[112:115]
	v_mfma_f32_16x16x32_bf16 v[104:107], v[174:177], v[182:185], v[104:107]
	v_mfma_f32_16x16x32_bf16 v[96:99], v[166:169], v[190:193], v[96:99]
	v_mfma_f32_16x16x32_bf16 v[88:91], v[174:177], v[190:193], v[88:91]
	v_mfma_f32_16x16x32_bf16 v[80:83], v[166:169], v[198:201], v[80:83]
	v_mfma_f32_16x16x32_bf16 v[72:75], v[174:177], v[198:201], v[72:75]
	v_mfma_f32_16x16x32_bf16 v[68:71], v[166:169], v[206:209], v[68:71]
	v_mfma_f32_16x16x32_bf16 v[64:67], v[174:177], v[206:209], v[64:67]
	s_barrier
	s_setprio 0
	s_add_i32 m0, s67, s59
	ds_read_b128 v[178:181], v145 offset:16384
	ds_read_b128 v[182:185], v145 offset:17408
	ds_read_b128 v[186:189], v145 offset:18432
	ds_read_b128 v[190:193], v145 offset:19456
	ds_read_b128 v[194:197], v145 offset:20480
	global_load_lds_dwordx4 v130, s[52:53]
	s_add_i32 m0, m0, 0x2000
	s_add_u32 s0, s52, 0x100000
	s_addc_u32 s1, s53, 0
	s_add_i32 s35, s68, s59
	global_load_lds_dwordx4 v134, s[52:53]
	s_mov_b32 m0, s35
	s_nop 0
	global_load_lds_dwordx4 v130, s[0:1]
	s_add_i32 m0, s35, 0x2000
	ds_read_b128 v[206:209], v145 offset:23552
	global_load_lds_dwordx4 v134, s[0:1]
	s_mov_b32 m0, s43
	ds_read_b128 v[202:205], v145 offset:22528
	global_load_lds_dwordx4 v128, s[54:55]
	s_mov_b32 m0, s62
	ds_read_b128 v[198:201], v145 offset:21504
	global_load_lds_dwordx4 v132, s[54:55]
	s_waitcnt vmcnt(8) lgkmcnt(0)
	s_setprio 3
	s_barrier
	v_mfma_f32_16x16x32_bf16 v[60:63], v[146:149], v[178:181], v[60:63]
	v_mfma_f32_16x16x32_bf16 v[56:59], v[154:157], v[178:181], v[56:59]
	v_mfma_f32_16x16x32_bf16 v[52:55], v[146:149], v[186:189], v[52:55]
	v_mfma_f32_16x16x32_bf16 v[44:47], v[154:157], v[186:189], v[44:47]
	v_mfma_f32_16x16x32_bf16 v[36:39], v[146:149], v[194:197], v[36:39]
	v_mfma_f32_16x16x32_bf16 v[28:31], v[154:157], v[194:197], v[28:31]
	v_mfma_f32_16x16x32_bf16 v[20:23], v[146:149], v[202:205], v[20:23]
	v_mfma_f32_16x16x32_bf16 v[12:15], v[154:157], v[202:205], v[12:15]
	v_mfma_f32_16x16x32_bf16 v[60:63], v[150:153], v[182:185], v[60:63]
	v_mfma_f32_16x16x32_bf16 v[56:59], v[158:161], v[182:185], v[56:59]
	v_mfma_f32_16x16x32_bf16 v[52:55], v[150:153], v[190:193], v[52:55]
	v_mfma_f32_16x16x32_bf16 v[44:47], v[158:161], v[190:193], v[44:47]
	v_mfma_f32_16x16x32_bf16 v[36:39], v[150:153], v[198:201], v[36:39]
	v_mfma_f32_16x16x32_bf16 v[28:31], v[158:161], v[198:201], v[28:31]
	v_mfma_f32_16x16x32_bf16 v[20:23], v[150:153], v[206:209], v[20:23]
	v_mfma_f32_16x16x32_bf16 v[12:15], v[158:161], v[206:209], v[12:15]
	v_mfma_f32_16x16x32_bf16 v[48:51], v[162:165], v[178:181], v[48:51]
	v_mfma_f32_16x16x32_bf16 v[40:43], v[170:173], v[178:181], v[40:43]
	v_mfma_f32_16x16x32_bf16 v[32:35], v[162:165], v[186:189], v[32:35]
	v_mfma_f32_16x16x32_bf16 v[24:27], v[170:173], v[186:189], v[24:27]
	v_mfma_f32_16x16x32_bf16 v[16:19], v[162:165], v[194:197], v[16:19]
	v_mfma_f32_16x16x32_bf16 v[8:11], v[170:173], v[194:197], v[8:11]
	v_mfma_f32_16x16x32_bf16 v[4:7], v[162:165], v[202:205], v[4:7]
	v_mfma_f32_16x16x32_bf16 v[0:3], v[170:173], v[202:205], v[0:3]
	v_mfma_f32_16x16x32_bf16 v[48:51], v[166:169], v[182:185], v[48:51]
	v_mfma_f32_16x16x32_bf16 v[40:43], v[174:177], v[182:185], v[40:43]
	v_mfma_f32_16x16x32_bf16 v[32:35], v[166:169], v[190:193], v[32:35]
	v_mfma_f32_16x16x32_bf16 v[24:27], v[174:177], v[190:193], v[24:27]
	v_mfma_f32_16x16x32_bf16 v[16:19], v[166:169], v[198:201], v[16:19]
	v_mfma_f32_16x16x32_bf16 v[8:11], v[174:177], v[198:201], v[8:11]
	v_mfma_f32_16x16x32_bf16 v[4:7], v[166:169], v[206:209], v[4:7]
	v_mfma_f32_16x16x32_bf16 v[0:3], v[174:177], v[206:209], v[0:3]
	s_barrier
	s_setprio 0
	s_add_i32 s35, 0, 0x18000
	s_add_i32 s37, 0, 0x1c000
	ds_read_b128 v[146:149], v216
	ds_read_b128 v[150:153], v216 offset:1024
	ds_read_b128 v[154:157], v216 offset:2048
	ds_read_b128 v[158:161], v216 offset:3072
	ds_read_b128 v[162:165], v217
	ds_read_b128 v[166:169], v217 offset:1024
	ds_read_b128 v[170:173], v217 offset:2048
	ds_read_b128 v[174:177], v217 offset:3072
	s_add_u32 s0, s54, 0x100000
	s_addc_u32 s1, s55, 0
	s_mov_b32 m0, s63
	ds_read_b128 v[178:181], v145 offset:32768
	ds_read_b128 v[182:185], v145 offset:33792
	ds_read_b128 v[186:189], v145 offset:34816
	ds_read_b128 v[190:193], v145 offset:35840
	ds_read_b128 v[194:197], v145 offset:36864
	ds_read_b128 v[198:201], v145 offset:37888
	ds_read_b128 v[202:205], v145 offset:38912
	global_load_lds_dwordx4 v128, s[0:1]
	s_mov_b32 m0, s64
	ds_read_b128 v[206:209], v145 offset:39936
	global_load_lds_dwordx4 v132, s[0:1]
	s_waitcnt vmcnt(8) lgkmcnt(0)
	s_setprio 3
	s_barrier
	v_mfma_f32_16x16x32_bf16 v[124:127], v[146:149], v[178:181], v[124:127]
	v_mfma_f32_16x16x32_bf16 v[120:123], v[154:157], v[178:181], v[120:123]
	v_mfma_f32_16x16x32_bf16 v[116:119], v[146:149], v[186:189], v[116:119]
	v_mfma_f32_16x16x32_bf16 v[108:111], v[154:157], v[186:189], v[108:111]
	v_mfma_f32_16x16x32_bf16 v[100:103], v[146:149], v[194:197], v[100:103]
	v_mfma_f32_16x16x32_bf16 v[92:95], v[154:157], v[194:197], v[92:95]
	v_mfma_f32_16x16x32_bf16 v[84:87], v[146:149], v[202:205], v[84:87]
	v_mfma_f32_16x16x32_bf16 v[76:79], v[154:157], v[202:205], v[76:79]
	v_mfma_f32_16x16x32_bf16 v[124:127], v[150:153], v[182:185], v[124:127]
	v_mfma_f32_16x16x32_bf16 v[120:123], v[158:161], v[182:185], v[120:123]
	v_mfma_f32_16x16x32_bf16 v[116:119], v[150:153], v[190:193], v[116:119]
	v_mfma_f32_16x16x32_bf16 v[108:111], v[158:161], v[190:193], v[108:111]
	v_mfma_f32_16x16x32_bf16 v[100:103], v[150:153], v[198:201], v[100:103]
	v_mfma_f32_16x16x32_bf16 v[92:95], v[158:161], v[198:201], v[92:95]
	v_mfma_f32_16x16x32_bf16 v[84:87], v[150:153], v[206:209], v[84:87]
	v_mfma_f32_16x16x32_bf16 v[76:79], v[158:161], v[206:209], v[76:79]
	v_mfma_f32_16x16x32_bf16 v[112:115], v[162:165], v[178:181], v[112:115]
	v_mfma_f32_16x16x32_bf16 v[104:107], v[170:173], v[178:181], v[104:107]
	v_mfma_f32_16x16x32_bf16 v[96:99], v[162:165], v[186:189], v[96:99]
	v_mfma_f32_16x16x32_bf16 v[88:91], v[170:173], v[186:189], v[88:91]
	v_mfma_f32_16x16x32_bf16 v[80:83], v[162:165], v[194:197], v[80:83]
	v_mfma_f32_16x16x32_bf16 v[72:75], v[170:173], v[194:197], v[72:75]
	v_mfma_f32_16x16x32_bf16 v[68:71], v[162:165], v[202:205], v[68:71]
	v_mfma_f32_16x16x32_bf16 v[64:67], v[170:173], v[202:205], v[64:67]
	v_mfma_f32_16x16x32_bf16 v[112:115], v[166:169], v[182:185], v[112:115]
	v_mfma_f32_16x16x32_bf16 v[104:107], v[174:177], v[182:185], v[104:107]
	v_mfma_f32_16x16x32_bf16 v[96:99], v[166:169], v[190:193], v[96:99]
	v_mfma_f32_16x16x32_bf16 v[88:91], v[174:177], v[190:193], v[88:91]
	v_mfma_f32_16x16x32_bf16 v[80:83], v[166:169], v[198:201], v[80:83]
	v_mfma_f32_16x16x32_bf16 v[72:75], v[174:177], v[198:201], v[72:75]
	v_mfma_f32_16x16x32_bf16 v[68:71], v[166:169], v[206:209], v[68:71]
	v_mfma_f32_16x16x32_bf16 v[64:67], v[174:177], v[206:209], v[64:67]
	s_barrier
	s_setprio 0
	s_add_u32 s100, s52, 0x80
	s_addc_u32 s101, s53, 0
	s_add_i32 m0, s35, s59
	ds_read_b128 v[178:181], v145 offset:49152
	ds_read_b128 v[182:185], v145 offset:50176
	ds_read_b128 v[186:189], v145 offset:51200
	ds_read_b128 v[190:193], v145 offset:52224
	global_load_lds_dwordx4 v130, s[100:101]
	s_add_i32 m0, m0, 0x2000
	s_add_u32 s0, s52, 0x100080
	s_addc_u32 s1, s53, 0
	s_add_i32 s35, s37, s59
	global_load_lds_dwordx4 v134, s[100:101]
	s_mov_b32 m0, s35
	ds_read_b128 v[206:209], v145 offset:56320
	global_load_lds_dwordx4 v130, s[0:1]
	s_add_i32 m0, s35, 0x2000
	ds_read_b128 v[202:205], v145 offset:55296
	global_load_lds_dwordx4 v134, s[0:1]
	s_add_u32 s100, s54, 0x80
	s_addc_u32 s101, s55, 0
	s_mov_b32 m0, s60
	ds_read_b128 v[198:201], v145 offset:54272
	global_load_lds_dwordx4 v128, s[100:101]
	s_mov_b32 m0, s65
	ds_read_b128 v[194:197], v145 offset:53248
	global_load_lds_dwordx4 v132, s[100:101]
	s_waitcnt vmcnt(8) lgkmcnt(0)
	s_setprio 3
	s_barrier
	v_mfma_f32_16x16x32_bf16 v[60:63], v[146:149], v[178:181], v[60:63]
	v_mfma_f32_16x16x32_bf16 v[56:59], v[154:157], v[178:181], v[56:59]
	v_mfma_f32_16x16x32_bf16 v[52:55], v[146:149], v[186:189], v[52:55]
	v_mfma_f32_16x16x32_bf16 v[44:47], v[154:157], v[186:189], v[44:47]
	v_mfma_f32_16x16x32_bf16 v[36:39], v[146:149], v[194:197], v[36:39]
	v_mfma_f32_16x16x32_bf16 v[28:31], v[154:157], v[194:197], v[28:31]
	v_mfma_f32_16x16x32_bf16 v[20:23], v[146:149], v[202:205], v[20:23]
	v_mfma_f32_16x16x32_bf16 v[12:15], v[154:157], v[202:205], v[12:15]
	v_mfma_f32_16x16x32_bf16 v[60:63], v[150:153], v[182:185], v[60:63]
	v_mfma_f32_16x16x32_bf16 v[56:59], v[158:161], v[182:185], v[56:59]
	v_mfma_f32_16x16x32_bf16 v[52:55], v[150:153], v[190:193], v[52:55]
	v_mfma_f32_16x16x32_bf16 v[44:47], v[158:161], v[190:193], v[44:47]
	v_mfma_f32_16x16x32_bf16 v[36:39], v[150:153], v[198:201], v[36:39]
	v_mfma_f32_16x16x32_bf16 v[28:31], v[158:161], v[198:201], v[28:31]
	v_mfma_f32_16x16x32_bf16 v[20:23], v[150:153], v[206:209], v[20:23]
	v_mfma_f32_16x16x32_bf16 v[12:15], v[158:161], v[206:209], v[12:15]
	v_mfma_f32_16x16x32_bf16 v[48:51], v[162:165], v[178:181], v[48:51]
	v_mfma_f32_16x16x32_bf16 v[40:43], v[170:173], v[178:181], v[40:43]
	v_mfma_f32_16x16x32_bf16 v[32:35], v[162:165], v[186:189], v[32:35]
	v_mfma_f32_16x16x32_bf16 v[24:27], v[170:173], v[186:189], v[24:27]
	v_mfma_f32_16x16x32_bf16 v[16:19], v[162:165], v[194:197], v[16:19]
	v_mfma_f32_16x16x32_bf16 v[8:11], v[170:173], v[194:197], v[8:11]
	v_mfma_f32_16x16x32_bf16 v[4:7], v[162:165], v[202:205], v[4:7]
	v_mfma_f32_16x16x32_bf16 v[0:3], v[170:173], v[202:205], v[0:3]
	v_mfma_f32_16x16x32_bf16 v[48:51], v[166:169], v[182:185], v[48:51]
	v_mfma_f32_16x16x32_bf16 v[40:43], v[174:177], v[182:185], v[40:43]
	v_mfma_f32_16x16x32_bf16 v[32:35], v[166:169], v[190:193], v[32:35]
	v_mfma_f32_16x16x32_bf16 v[24:27], v[174:177], v[190:193], v[24:27]
	v_mfma_f32_16x16x32_bf16 v[16:19], v[166:169], v[198:201], v[16:19]
	v_mfma_f32_16x16x32_bf16 v[8:11], v[174:177], v[198:201], v[8:11]
	v_mfma_f32_16x16x32_bf16 v[4:7], v[166:169], v[206:209], v[4:7]
	v_mfma_f32_16x16x32_bf16 v[0:3], v[174:177], v[206:209], v[0:3]
	s_barrier
	s_setprio 0
	s_cmpk_gt_u32 s13, 0xa9
	s_mov_b32 s35, s4
	s_cbranch_scc1 .LBB0_432

.LBB0_677:
	ds_read_b128 v[156:159], v152
	ds_read_b128 v[160:163], v152 offset:1024
	ds_read_b128 v[164:167], v152 offset:2048
	ds_read_b128 v[168:171], v152 offset:3072
	ds_read_b128 v[172:175], v153
	ds_read_b128 v[176:179], v153 offset:1024
	ds_read_b128 v[180:183], v153 offset:2048
	ds_read_b128 v[184:187], v153 offset:3072
	s_add_u32 s0, s36, 0xfff00080
	s_addc_u32 s1, s37, -1
	s_cmp_eq_u32 s61, 60
	s_cselect_b32 s41, s56, s1
	s_cselect_b32 s40, s57, s0
	s_cselect_b32 s39, s15, s60
	s_cselect_b32 s38, s58, s59
	s_add_i32 m0, s31, 0xc000
	ds_read_b128 v[188:191], v154
	ds_read_b128 v[192:195], v154 offset:1024
	ds_read_b128 v[196:199], v154 offset:2048
	ds_read_b128 v[200:203], v154 offset:3072
	ds_read_b128 v[204:207], v154 offset:4096
	ds_read_b128 v[208:211], v154 offset:5120
	ds_read_b128 v[212:215], v154 offset:6144
	global_load_lds_dwordx4 v138, s[36:37]
	s_add_i32 m0, s31, 0xe000
	ds_read_b128 v[216:219], v154 offset:7168
	global_load_lds_dwordx4 v140, s[36:37]
	s_waitcnt vmcnt(8) lgkmcnt(0)
	s_setprio 3
	s_barrier
	v_mfma_f32_16x16x32_bf16 v[124:127], v[156:159], v[188:191], v[124:127]
	v_mfma_f32_16x16x32_bf16 v[120:123], v[164:167], v[188:191], v[120:123]
	v_mfma_f32_16x16x32_bf16 v[108:111], v[156:159], v[196:199], v[108:111]
	v_mfma_f32_16x16x32_bf16 v[104:107], v[164:167], v[196:199], v[104:107]
	v_mfma_f32_16x16x32_bf16 v[92:95], v[156:159], v[204:207], v[92:95]
	v_mfma_f32_16x16x32_bf16 v[88:91], v[164:167], v[204:207], v[88:91]
	v_mfma_f32_16x16x32_bf16 v[76:79], v[156:159], v[212:215], v[76:79]
	v_mfma_f32_16x16x32_bf16 v[72:75], v[164:167], v[212:215], v[72:75]
	v_mfma_f32_16x16x32_bf16 v[124:127], v[160:163], v[192:195], v[124:127]
	v_mfma_f32_16x16x32_bf16 v[120:123], v[168:171], v[192:195], v[120:123]
	v_mfma_f32_16x16x32_bf16 v[108:111], v[160:163], v[200:203], v[108:111]
	v_mfma_f32_16x16x32_bf16 v[104:107], v[168:171], v[200:203], v[104:107]
	v_mfma_f32_16x16x32_bf16 v[92:95], v[160:163], v[208:211], v[92:95]
	v_mfma_f32_16x16x32_bf16 v[88:91], v[168:171], v[208:211], v[88:91]
	v_mfma_f32_16x16x32_bf16 v[76:79], v[160:163], v[216:219], v[76:79]
	v_mfma_f32_16x16x32_bf16 v[72:75], v[168:171], v[216:219], v[72:75]
	v_mfma_f32_16x16x32_bf16 v[116:119], v[172:175], v[188:191], v[116:119]
	v_mfma_f32_16x16x32_bf16 v[112:115], v[180:183], v[188:191], v[112:115]
	v_mfma_f32_16x16x32_bf16 v[100:103], v[172:175], v[196:199], v[100:103]
	v_mfma_f32_16x16x32_bf16 v[96:99], v[180:183], v[196:199], v[96:99]
	v_mfma_f32_16x16x32_bf16 v[84:87], v[172:175], v[204:207], v[84:87]
	v_mfma_f32_16x16x32_bf16 v[80:83], v[180:183], v[204:207], v[80:83]
	v_mfma_f32_16x16x32_bf16 v[68:71], v[172:175], v[212:215], v[68:71]
	v_mfma_f32_16x16x32_bf16 v[64:67], v[180:183], v[212:215], v[64:67]
	v_mfma_f32_16x16x32_bf16 v[116:119], v[176:179], v[192:195], v[116:119]
	v_mfma_f32_16x16x32_bf16 v[112:115], v[184:187], v[192:195], v[112:115]
	v_mfma_f32_16x16x32_bf16 v[100:103], v[176:179], v[200:203], v[100:103]
	v_mfma_f32_16x16x32_bf16 v[96:99], v[184:187], v[200:203], v[96:99]
	v_mfma_f32_16x16x32_bf16 v[84:87], v[176:179], v[208:211], v[84:87]
	v_mfma_f32_16x16x32_bf16 v[80:83], v[184:187], v[208:211], v[80:83]
	v_mfma_f32_16x16x32_bf16 v[68:71], v[176:179], v[216:219], v[68:71]
	v_mfma_f32_16x16x32_bf16 v[64:67], v[184:187], v[216:219], v[64:67]
	s_barrier
	s_setprio 0
	s_add_i32 m0, s51, s43
	ds_read_b128 v[188:191], v154 offset:16384
	ds_read_b128 v[192:195], v154 offset:17408
	ds_read_b128 v[196:199], v154 offset:18432
	ds_read_b128 v[200:203], v154 offset:19456
	ds_read_b128 v[204:207], v154 offset:20480
	global_load_lds_dwordx4 v130, s[38:39]
	s_add_i32 m0, m0, 0x2000
	s_add_u32 s0, s38, 0x100000
	s_addc_u32 s1, s39, 0
	s_add_i32 s62, s52, s43
	global_load_lds_dwordx4 v134, s[38:39]
	s_mov_b32 m0, s62
	s_nop 0
	global_load_lds_dwordx4 v130, s[0:1]
	s_add_i32 m0, s62, 0x2000
	ds_read_b128 v[216:219], v154 offset:23552
	global_load_lds_dwordx4 v134, s[0:1]
	s_mov_b32 m0, s31
	ds_read_b128 v[212:215], v154 offset:22528
	global_load_lds_dwordx4 v128, s[40:41]
	s_mov_b32 m0, s35
	ds_read_b128 v[208:211], v154 offset:21504
	global_load_lds_dwordx4 v132, s[40:41]
	s_waitcnt vmcnt(8) lgkmcnt(0)
	s_setprio 3
	s_barrier
	v_mfma_f32_16x16x32_bf16 v[60:63], v[156:159], v[188:191], v[60:63]
	v_mfma_f32_16x16x32_bf16 v[56:59], v[164:167], v[188:191], v[56:59]
	v_mfma_f32_16x16x32_bf16 v[44:47], v[156:159], v[196:199], v[44:47]
	v_mfma_f32_16x16x32_bf16 v[40:43], v[164:167], v[196:199], v[40:43]
	v_mfma_f32_16x16x32_bf16 v[28:31], v[156:159], v[204:207], v[28:31]
	v_mfma_f32_16x16x32_bf16 v[24:27], v[164:167], v[204:207], v[24:27]
	v_mfma_f32_16x16x32_bf16 v[12:15], v[156:159], v[212:215], v[12:15]
	v_mfma_f32_16x16x32_bf16 v[8:11], v[164:167], v[212:215], v[8:11]
	v_mfma_f32_16x16x32_bf16 v[60:63], v[160:163], v[192:195], v[60:63]
	v_mfma_f32_16x16x32_bf16 v[56:59], v[168:171], v[192:195], v[56:59]
	v_mfma_f32_16x16x32_bf16 v[44:47], v[160:163], v[200:203], v[44:47]
	v_mfma_f32_16x16x32_bf16 v[40:43], v[168:171], v[200:203], v[40:43]
	v_mfma_f32_16x16x32_bf16 v[28:31], v[160:163], v[208:211], v[28:31]
	v_mfma_f32_16x16x32_bf16 v[24:27], v[168:171], v[208:211], v[24:27]
	v_mfma_f32_16x16x32_bf16 v[12:15], v[160:163], v[216:219], v[12:15]
	v_mfma_f32_16x16x32_bf16 v[8:11], v[168:171], v[216:219], v[8:11]
	v_mfma_f32_16x16x32_bf16 v[52:55], v[172:175], v[188:191], v[52:55]
	v_mfma_f32_16x16x32_bf16 v[48:51], v[180:183], v[188:191], v[48:51]
	v_mfma_f32_16x16x32_bf16 v[36:39], v[172:175], v[196:199], v[36:39]
	v_mfma_f32_16x16x32_bf16 v[32:35], v[180:183], v[196:199], v[32:35]
	v_mfma_f32_16x16x32_bf16 v[20:23], v[172:175], v[204:207], v[20:23]
	v_mfma_f32_16x16x32_bf16 v[16:19], v[180:183], v[204:207], v[16:19]
	v_mfma_f32_16x16x32_bf16 v[4:7], v[172:175], v[212:215], v[4:7]
	v_mfma_f32_16x16x32_bf16 v[0:3], v[180:183], v[212:215], v[0:3]
	v_mfma_f32_16x16x32_bf16 v[52:55], v[176:179], v[192:195], v[52:55]
	v_mfma_f32_16x16x32_bf16 v[48:51], v[184:187], v[192:195], v[48:51]
	v_mfma_f32_16x16x32_bf16 v[36:39], v[176:179], v[200:203], v[36:39]
	v_mfma_f32_16x16x32_bf16 v[32:35], v[184:187], v[200:203], v[32:35]
	v_mfma_f32_16x16x32_bf16 v[20:23], v[176:179], v[208:211], v[20:23]
	v_mfma_f32_16x16x32_bf16 v[16:19], v[184:187], v[208:211], v[16:19]
	v_mfma_f32_16x16x32_bf16 v[4:7], v[176:179], v[216:219], v[4:7]
	v_mfma_f32_16x16x32_bf16 v[0:3], v[184:187], v[216:219], v[0:3]
	s_barrier
	s_setprio 0
	s_add_i32 s62, 0, 0x18000
	s_add_i32 s63, 0, 0x1c000
	ds_read_b128 v[156:159], v226
	ds_read_b128 v[160:163], v226 offset:1024
	ds_read_b128 v[164:167], v226 offset:2048
	ds_read_b128 v[168:171], v226 offset:3072
	ds_read_b128 v[172:175], v227
	ds_read_b128 v[176:179], v227 offset:1024
	ds_read_b128 v[180:183], v227 offset:2048
	ds_read_b128 v[184:187], v227 offset:3072
	s_add_u32 s0, s40, 0x100000
	s_addc_u32 s1, s41, 0
	s_mov_b32 m0, s44
	ds_read_b128 v[188:191], v154 offset:32768
	ds_read_b128 v[192:195], v154 offset:33792
	ds_read_b128 v[196:199], v154 offset:34816
	ds_read_b128 v[200:203], v154 offset:35840
	ds_read_b128 v[204:207], v154 offset:36864
	ds_read_b128 v[208:211], v154 offset:37888
	ds_read_b128 v[212:215], v154 offset:38912
	global_load_lds_dwordx4 v128, s[0:1]
	s_mov_b32 m0, s45
	ds_read_b128 v[216:219], v154 offset:39936
	global_load_lds_dwordx4 v132, s[0:1]
	s_waitcnt vmcnt(8) lgkmcnt(0)
	s_setprio 3
	s_barrier
	v_mfma_f32_16x16x32_bf16 v[124:127], v[156:159], v[188:191], v[124:127]
	v_mfma_f32_16x16x32_bf16 v[120:123], v[164:167], v[188:191], v[120:123]
	v_mfma_f32_16x16x32_bf16 v[108:111], v[156:159], v[196:199], v[108:111]
	v_mfma_f32_16x16x32_bf16 v[104:107], v[164:167], v[196:199], v[104:107]
	v_mfma_f32_16x16x32_bf16 v[92:95], v[156:159], v[204:207], v[92:95]
	v_mfma_f32_16x16x32_bf16 v[88:91], v[164:167], v[204:207], v[88:91]
	v_mfma_f32_16x16x32_bf16 v[76:79], v[156:159], v[212:215], v[76:79]
	v_mfma_f32_16x16x32_bf16 v[72:75], v[164:167], v[212:215], v[72:75]
	v_mfma_f32_16x16x32_bf16 v[124:127], v[160:163], v[192:195], v[124:127]
	v_mfma_f32_16x16x32_bf16 v[120:123], v[168:171], v[192:195], v[120:123]
	v_mfma_f32_16x16x32_bf16 v[108:111], v[160:163], v[200:203], v[108:111]
	v_mfma_f32_16x16x32_bf16 v[104:107], v[168:171], v[200:203], v[104:107]
	v_mfma_f32_16x16x32_bf16 v[92:95], v[160:163], v[208:211], v[92:95]
	v_mfma_f32_16x16x32_bf16 v[88:91], v[168:171], v[208:211], v[88:91]
	v_mfma_f32_16x16x32_bf16 v[76:79], v[160:163], v[216:219], v[76:79]
	v_mfma_f32_16x16x32_bf16 v[72:75], v[168:171], v[216:219], v[72:75]
	v_mfma_f32_16x16x32_bf16 v[116:119], v[172:175], v[188:191], v[116:119]
	v_mfma_f32_16x16x32_bf16 v[112:115], v[180:183], v[188:191], v[112:115]
	v_mfma_f32_16x16x32_bf16 v[100:103], v[172:175], v[196:199], v[100:103]
	v_mfma_f32_16x16x32_bf16 v[96:99], v[180:183], v[196:199], v[96:99]
	v_mfma_f32_16x16x32_bf16 v[84:87], v[172:175], v[204:207], v[84:87]
	v_mfma_f32_16x16x32_bf16 v[80:83], v[180:183], v[204:207], v[80:83]
	v_mfma_f32_16x16x32_bf16 v[68:71], v[172:175], v[212:215], v[68:71]
	v_mfma_f32_16x16x32_bf16 v[64:67], v[180:183], v[212:215], v[64:67]
	v_mfma_f32_16x16x32_bf16 v[116:119], v[176:179], v[192:195], v[116:119]
	v_mfma_f32_16x16x32_bf16 v[112:115], v[184:187], v[192:195], v[112:115]
	v_mfma_f32_16x16x32_bf16 v[100:103], v[176:179], v[200:203], v[100:103]
	v_mfma_f32_16x16x32_bf16 v[96:99], v[184:187], v[200:203], v[96:99]
	v_mfma_f32_16x16x32_bf16 v[84:87], v[176:179], v[208:211], v[84:87]
	v_mfma_f32_16x16x32_bf16 v[80:83], v[184:187], v[208:211], v[80:83]
	v_mfma_f32_16x16x32_bf16 v[68:71], v[176:179], v[216:219], v[68:71]
	v_mfma_f32_16x16x32_bf16 v[64:67], v[184:187], v[216:219], v[64:67]
	s_barrier
	s_setprio 0
	s_add_u32 s100, s38, 0x80
	s_addc_u32 s101, s39, 0
	s_add_i32 m0, s62, s43
	ds_read_b128 v[188:191], v154 offset:49152
	ds_read_b128 v[192:195], v154 offset:50176
	ds_read_b128 v[196:199], v154 offset:51200
	ds_read_b128 v[200:203], v154 offset:52224
	global_load_lds_dwordx4 v130, s[100:101]
	s_add_i32 m0, m0, 0x2000
	s_add_u32 s0, s38, 0x100080
	s_addc_u32 s1, s39, 0
	s_add_i32 s38, s63, s43
	global_load_lds_dwordx4 v134, s[100:101]
	s_mov_b32 m0, s38
	ds_read_b128 v[216:219], v154 offset:56320
	global_load_lds_dwordx4 v130, s[0:1]
	s_add_i32 m0, s38, 0x2000
	ds_read_b128 v[212:215], v154 offset:55296
	global_load_lds_dwordx4 v134, s[0:1]
	s_add_u32 s100, s40, 0x80
	s_addc_u32 s101, s41, 0
	s_mov_b32 m0, s46
	ds_read_b128 v[208:211], v154 offset:54272
	global_load_lds_dwordx4 v128, s[100:101]
	s_mov_b32 m0, s47
	ds_read_b128 v[204:207], v154 offset:53248
	global_load_lds_dwordx4 v132, s[100:101]
	s_waitcnt vmcnt(8) lgkmcnt(0)
	s_setprio 3
	s_barrier
	v_mfma_f32_16x16x32_bf16 v[60:63], v[156:159], v[188:191], v[60:63]
	v_mfma_f32_16x16x32_bf16 v[56:59], v[164:167], v[188:191], v[56:59]
	v_mfma_f32_16x16x32_bf16 v[44:47], v[156:159], v[196:199], v[44:47]
	v_mfma_f32_16x16x32_bf16 v[40:43], v[164:167], v[196:199], v[40:43]
	v_mfma_f32_16x16x32_bf16 v[28:31], v[156:159], v[204:207], v[28:31]
	v_mfma_f32_16x16x32_bf16 v[24:27], v[164:167], v[204:207], v[24:27]
	v_mfma_f32_16x16x32_bf16 v[12:15], v[156:159], v[212:215], v[12:15]
	v_mfma_f32_16x16x32_bf16 v[8:11], v[164:167], v[212:215], v[8:11]
	v_mfma_f32_16x16x32_bf16 v[60:63], v[160:163], v[192:195], v[60:63]
	v_mfma_f32_16x16x32_bf16 v[56:59], v[168:171], v[192:195], v[56:59]
	v_mfma_f32_16x16x32_bf16 v[44:47], v[160:163], v[200:203], v[44:47]
	v_mfma_f32_16x16x32_bf16 v[40:43], v[168:171], v[200:203], v[40:43]
	v_mfma_f32_16x16x32_bf16 v[28:31], v[160:163], v[208:211], v[28:31]
	v_mfma_f32_16x16x32_bf16 v[24:27], v[168:171], v[208:211], v[24:27]
	v_mfma_f32_16x16x32_bf16 v[12:15], v[160:163], v[216:219], v[12:15]
	v_mfma_f32_16x16x32_bf16 v[8:11], v[168:171], v[216:219], v[8:11]
	v_mfma_f32_16x16x32_bf16 v[52:55], v[172:175], v[188:191], v[52:55]
	v_mfma_f32_16x16x32_bf16 v[48:51], v[180:183], v[188:191], v[48:51]
	v_mfma_f32_16x16x32_bf16 v[36:39], v[172:175], v[196:199], v[36:39]
	v_mfma_f32_16x16x32_bf16 v[32:35], v[180:183], v[196:199], v[32:35]
	v_mfma_f32_16x16x32_bf16 v[20:23], v[172:175], v[204:207], v[20:23]
	v_mfma_f32_16x16x32_bf16 v[16:19], v[180:183], v[204:207], v[16:19]
	v_mfma_f32_16x16x32_bf16 v[4:7], v[172:175], v[212:215], v[4:7]
	v_mfma_f32_16x16x32_bf16 v[0:3], v[180:183], v[212:215], v[0:3]
	v_mfma_f32_16x16x32_bf16 v[52:55], v[176:179], v[192:195], v[52:55]
	v_mfma_f32_16x16x32_bf16 v[48:51], v[184:187], v[192:195], v[48:51]
	v_mfma_f32_16x16x32_bf16 v[36:39], v[176:179], v[200:203], v[36:39]
	v_mfma_f32_16x16x32_bf16 v[32:35], v[184:187], v[200:203], v[32:35]
	v_mfma_f32_16x16x32_bf16 v[20:23], v[176:179], v[208:211], v[20:23]
	v_mfma_f32_16x16x32_bf16 v[16:19], v[184:187], v[208:211], v[16:19]
	v_mfma_f32_16x16x32_bf16 v[4:7], v[176:179], v[216:219], v[4:7]
	v_mfma_f32_16x16x32_bf16 v[0:3], v[184:187], v[216:219], v[0:3]
	s_barrier
	s_setprio 0
	s_add_u32 s36, s36, 0x100
	s_addc_u32 s37, s37, 0
	s_add_i32 s61, s61, 2
	s_add_u32 s59, s59, 0x100
	s_addc_u32 s60, s60, 0
	s_cmp_gt_u32 s61, 61
	s_cbranch_scc0 .LBB0_677
	s_and_b64 vcc, exec, s[12:13]
	s_cbranch_vccz .LBB0_680
	s_barrier

.LBB0_705:
	ds_read_b128 v[24:27], v191
	ds_read_b128 v[28:31], v191 offset:1024
	ds_read_b128 v[16:19], v191 offset:2048
	ds_read_b128 v[20:23], v191 offset:3072
	ds_read_b128 v[8:11], v192
	ds_read_b128 v[12:15], v192 offset:1024
	ds_read_b128 v[0:3], v192 offset:2048
	ds_read_b128 v[4:7], v192 offset:3072
	s_add_u32 s0, s44, 0xfff80080
	s_addc_u32 s1, s45, -1
	s_cmp_eq_u32 s70, 28
	s_cselect_b32 s49, s60, s1
	s_cselect_b32 s48, s66, s0
	s_cselect_b32 s47, s31, s69
	s_cselect_b32 s46, s67, s68
	s_add_i32 m0, s41, 0xc000
	ds_read_b128 v[178:181], v193
	ds_read_b128 v[182:185], v193 offset:1024
	ds_read_b128 v[194:197], v193 offset:2048
	ds_read_b128 v[198:201], v193 offset:3072
	ds_read_b128 v[208:211], v193 offset:4096
	ds_read_b128 v[212:215], v193 offset:5120
	ds_read_b128 v[216:219], v193 offset:6144
	global_load_lds_dwordx4 v170, s[44:45]
	s_add_i32 m0, s41, 0xe000
	ds_read_b128 v[220:223], v193 offset:7168
	global_load_lds_dwordx4 v172, s[44:45]
	s_waitcnt vmcnt(8) lgkmcnt(0)
	s_setprio 3
	s_barrier
	v_mfma_scale_f32_16x16x128_f8f6f4 v[156:159], v[24:31], v[178:185], v[156:159], v186, v186 op_sel_hi:[0,0,0]
	v_mfma_scale_f32_16x16x128_f8f6f4 v[152:155], v[16:23], v[178:185], v[152:155], v186, v186 op_sel_hi:[0,0,0]
	v_mfma_scale_f32_16x16x128_f8f6f4 v[140:143], v[24:31], v[194:201], v[140:143], v186, v186 op_sel_hi:[0,0,0]
	v_mfma_scale_f32_16x16x128_f8f6f4 v[136:139], v[16:23], v[194:201], v[136:139], v186, v186 op_sel_hi:[0,0,0]
	v_mfma_scale_f32_16x16x128_f8f6f4 v[124:127], v[24:31], v[208:215], v[124:127], v186, v186 op_sel_hi:[0,0,0]
	v_mfma_scale_f32_16x16x128_f8f6f4 v[120:123], v[16:23], v[208:215], v[120:123], v186, v186 op_sel_hi:[0,0,0]
	v_mfma_scale_f32_16x16x128_f8f6f4 v[108:111], v[24:31], v[216:223], v[108:111], v186, v186 op_sel_hi:[0,0,0]
	v_mfma_scale_f32_16x16x128_f8f6f4 v[104:107], v[16:23], v[216:223], v[104:107], v186, v186 op_sel_hi:[0,0,0]
	v_mfma_scale_f32_16x16x128_f8f6f4 v[148:151], v[8:15], v[178:185], v[148:151], v186, v186 op_sel_hi:[0,0,0]
	v_mfma_scale_f32_16x16x128_f8f6f4 v[144:147], v[0:7], v[178:185], v[144:147], v186, v186 op_sel_hi:[0,0,0]
	v_mfma_scale_f32_16x16x128_f8f6f4 v[132:135], v[8:15], v[194:201], v[132:135], v186, v186 op_sel_hi:[0,0,0]
	v_mfma_scale_f32_16x16x128_f8f6f4 v[128:131], v[0:7], v[194:201], v[128:131], v186, v186 op_sel_hi:[0,0,0]
	v_mfma_scale_f32_16x16x128_f8f6f4 v[116:119], v[8:15], v[208:215], v[116:119], v186, v186 op_sel_hi:[0,0,0]
	v_mfma_scale_f32_16x16x128_f8f6f4 v[112:115], v[0:7], v[208:215], v[112:115], v186, v186 op_sel_hi:[0,0,0]
	v_mfma_scale_f32_16x16x128_f8f6f4 v[100:103], v[8:15], v[216:223], v[100:103], v186, v186 op_sel_hi:[0,0,0]
	v_mfma_scale_f32_16x16x128_f8f6f4 v[96:99], v[0:7], v[216:223], v[96:99], v186, v186 op_sel_hi:[0,0,0]
	s_barrier
	s_setprio 0
	s_add_i32 m0, s58, s51
	ds_read_b128 v[194:197], v193 offset:16384
	ds_read_b128 v[198:201], v193 offset:17408
	ds_read_b128 v[208:211], v193 offset:18432
	ds_read_b128 v[212:215], v193 offset:19456
	ds_read_b128 v[216:219], v193 offset:20480
	global_load_lds_dwordx4 v162, s[46:47]
	s_add_i32 m0, m0, 0x2000
	s_add_u32 s0, s46, 0x80000
	s_addc_u32 s1, s47, 0
	s_add_i32 s71, s59, s51
	global_load_lds_dwordx4 v166, s[46:47]
	s_mov_b32 m0, s71
	s_nop 0
	global_load_lds_dwordx4 v162, s[0:1]
	s_add_i32 m0, s71, 0x2000
	ds_read_b128 v[228:231], v193 offset:23552
	global_load_lds_dwordx4 v166, s[0:1]
	s_mov_b32 m0, s41
	ds_read_b128 v[224:227], v193 offset:22528
	global_load_lds_dwordx4 v160, s[48:49]
	s_mov_b32 m0, s43
	ds_read_b128 v[220:223], v193 offset:21504
	global_load_lds_dwordx4 v164, s[48:49]
	s_waitcnt vmcnt(8) lgkmcnt(0)
	s_setprio 3
	s_barrier
	v_mfma_scale_f32_16x16x128_f8f6f4 v[92:95], v[24:31], v[194:201], v[92:95], v186, v186 op_sel_hi:[0,0,0]
	v_mfma_scale_f32_16x16x128_f8f6f4 v[88:91], v[16:23], v[194:201], v[88:91], v186, v186 op_sel_hi:[0,0,0]
	v_mfma_scale_f32_16x16x128_f8f6f4 v[80:83], v[24:31], v[208:215], v[80:83], v186, v186 op_sel_hi:[0,0,0]
	v_mfma_scale_f32_16x16x128_f8f6f4 v[72:75], v[16:23], v[208:215], v[72:75], v186, v186 op_sel_hi:[0,0,0]
	v_mfma_scale_f32_16x16x128_f8f6f4 v[64:67], v[24:31], v[216:223], v[64:67], v186, v186 op_sel_hi:[0,0,0]
	v_mfma_scale_f32_16x16x128_f8f6f4 v[56:59], v[16:23], v[216:223], v[56:59], v186, v186 op_sel_hi:[0,0,0]
	v_mfma_scale_f32_16x16x128_f8f6f4 v[48:51], v[24:31], v[224:231], v[48:51], v186, v186 op_sel_hi:[0,0,0]
	v_mfma_scale_f32_16x16x128_f8f6f4 v[40:43], v[16:23], v[224:231], v[40:43], v186, v186 op_sel_hi:[0,0,0]
	v_mfma_scale_f32_16x16x128_f8f6f4 v[84:87], v[8:15], v[194:201], v[84:87], v186, v186 op_sel_hi:[0,0,0]
	v_mfma_scale_f32_16x16x128_f8f6f4 v[76:79], v[0:7], v[194:201], v[76:79], v186, v186 op_sel_hi:[0,0,0]
	v_mfma_scale_f32_16x16x128_f8f6f4 v[68:71], v[8:15], v[208:215], v[68:71], v186, v186 op_sel_hi:[0,0,0]
	v_mfma_scale_f32_16x16x128_f8f6f4 v[60:63], v[0:7], v[208:215], v[60:63], v186, v186 op_sel_hi:[0,0,0]
	v_mfma_scale_f32_16x16x128_f8f6f4 v[52:55], v[8:15], v[216:223], v[52:55], v186, v186 op_sel_hi:[0,0,0]
	v_mfma_scale_f32_16x16x128_f8f6f4 v[44:47], v[0:7], v[216:223], v[44:47], v186, v186 op_sel_hi:[0,0,0]
	v_mfma_scale_f32_16x16x128_f8f6f4 v[36:39], v[8:15], v[224:231], v[36:39], v186, v186 op_sel_hi:[0,0,0]
	v_mfma_scale_f32_16x16x128_f8f6f4 v[32:35], v[0:7], v[224:231], v[32:35], v186, v186 op_sel_hi:[0,0,0]
	s_barrier
	s_setprio 0
	s_add_i32 s71, 0, 0x18000
	s_add_i32 s73, 0, 0x1c000
	ds_read_b128 v[0:3], v202
	ds_read_b128 v[4:7], v202 offset:1024
	ds_read_b128 v[8:11], v202 offset:2048
	ds_read_b128 v[12:15], v202 offset:3072
	ds_read_b128 v[16:19], v203
	ds_read_b128 v[20:23], v203 offset:1024
	ds_read_b128 v[24:27], v203 offset:2048
	ds_read_b128 v[28:31], v203 offset:3072
	s_add_u32 s0, s48, 0x80000
	s_addc_u32 s1, s49, 0
	s_mov_b32 m0, s52
	ds_read_b128 v[194:197], v193 offset:32768
	ds_read_b128 v[198:201], v193 offset:33792
	ds_read_b128 v[208:211], v193 offset:34816
	ds_read_b128 v[212:215], v193 offset:35840
	ds_read_b128 v[216:219], v193 offset:36864
	ds_read_b128 v[220:223], v193 offset:37888
	ds_read_b128 v[224:227], v193 offset:38912
	global_load_lds_dwordx4 v160, s[0:1]
	s_mov_b32 m0, s53
	ds_read_b128 v[228:231], v193 offset:39936
	global_load_lds_dwordx4 v164, s[0:1]
	s_waitcnt vmcnt(8) lgkmcnt(0)
	s_setprio 3
	s_barrier
	v_mfma_scale_f32_16x16x128_f8f6f4 v[156:159], v[0:7], v[194:201], v[156:159], v186, v186 op_sel_hi:[0,0,0]
	v_mfma_scale_f32_16x16x128_f8f6f4 v[152:155], v[8:15], v[194:201], v[152:155], v186, v186 op_sel_hi:[0,0,0]
	v_mfma_scale_f32_16x16x128_f8f6f4 v[140:143], v[0:7], v[208:215], v[140:143], v186, v186 op_sel_hi:[0,0,0]
	v_mfma_scale_f32_16x16x128_f8f6f4 v[136:139], v[8:15], v[208:215], v[136:139], v186, v186 op_sel_hi:[0,0,0]
	v_mfma_scale_f32_16x16x128_f8f6f4 v[124:127], v[0:7], v[216:223], v[124:127], v186, v186 op_sel_hi:[0,0,0]
	v_mfma_scale_f32_16x16x128_f8f6f4 v[120:123], v[8:15], v[216:223], v[120:123], v186, v186 op_sel_hi:[0,0,0]
	v_mfma_scale_f32_16x16x128_f8f6f4 v[108:111], v[0:7], v[224:231], v[108:111], v186, v186 op_sel_hi:[0,0,0]
	v_mfma_scale_f32_16x16x128_f8f6f4 v[104:107], v[8:15], v[224:231], v[104:107], v186, v186 op_sel_hi:[0,0,0]
	v_mfma_scale_f32_16x16x128_f8f6f4 v[148:151], v[16:23], v[194:201], v[148:151], v186, v186 op_sel_hi:[0,0,0]
	v_mfma_scale_f32_16x16x128_f8f6f4 v[144:147], v[24:31], v[194:201], v[144:147], v186, v186 op_sel_hi:[0,0,0]
	v_mfma_scale_f32_16x16x128_f8f6f4 v[132:135], v[16:23], v[208:215], v[132:135], v186, v186 op_sel_hi:[0,0,0]
	v_mfma_scale_f32_16x16x128_f8f6f4 v[128:131], v[24:31], v[208:215], v[128:131], v186, v186 op_sel_hi:[0,0,0]
	v_mfma_scale_f32_16x16x128_f8f6f4 v[116:119], v[16:23], v[216:223], v[116:119], v186, v186 op_sel_hi:[0,0,0]
	v_mfma_scale_f32_16x16x128_f8f6f4 v[112:115], v[24:31], v[216:223], v[112:115], v186, v186 op_sel_hi:[0,0,0]
	v_mfma_scale_f32_16x16x128_f8f6f4 v[100:103], v[16:23], v[224:231], v[100:103], v186, v186 op_sel_hi:[0,0,0]
	v_mfma_scale_f32_16x16x128_f8f6f4 v[96:99], v[24:31], v[224:231], v[96:99], v186, v186 op_sel_hi:[0,0,0]
	s_barrier
	s_setprio 0
	s_add_u32 s100, s46, 0x80
	s_addc_u32 s101, s47, 0
	s_add_i32 m0, s71, s51
	ds_read_b128 v[194:197], v193 offset:49152
	ds_read_b128 v[198:201], v193 offset:50176
	ds_read_b128 v[208:211], v193 offset:51200
	ds_read_b128 v[212:215], v193 offset:52224
	global_load_lds_dwordx4 v162, s[100:101]
	s_add_i32 m0, m0, 0x2000
	s_add_u32 s0, s46, 0x80080
	s_addc_u32 s1, s47, 0
	s_add_i32 s46, s73, s51
	global_load_lds_dwordx4 v166, s[100:101]
	s_mov_b32 m0, s46
	ds_read_b128 v[228:231], v193 offset:56320
	global_load_lds_dwordx4 v162, s[0:1]
	s_add_i32 m0, s46, 0x2000
	ds_read_b128 v[224:227], v193 offset:55296
	global_load_lds_dwordx4 v166, s[0:1]
	s_add_u32 s100, s48, 0x80
	s_addc_u32 s101, s49, 0
	s_mov_b32 m0, s55
	ds_read_b128 v[220:223], v193 offset:54272
	global_load_lds_dwordx4 v160, s[100:101]
	s_mov_b32 m0, s56
	ds_read_b128 v[216:219], v193 offset:53248
	global_load_lds_dwordx4 v164, s[100:101]
	s_waitcnt vmcnt(8) lgkmcnt(0)
	s_setprio 3
	s_barrier
	v_mfma_scale_f32_16x16x128_f8f6f4 v[92:95], v[0:7], v[194:201], v[92:95], v186, v186 op_sel_hi:[0,0,0]
	v_mfma_scale_f32_16x16x128_f8f6f4 v[88:91], v[8:15], v[194:201], v[88:91], v186, v186 op_sel_hi:[0,0,0]
	v_mfma_scale_f32_16x16x128_f8f6f4 v[80:83], v[0:7], v[208:215], v[80:83], v186, v186 op_sel_hi:[0,0,0]
	v_mfma_scale_f32_16x16x128_f8f6f4 v[72:75], v[8:15], v[208:215], v[72:75], v186, v186 op_sel_hi:[0,0,0]
	v_mfma_scale_f32_16x16x128_f8f6f4 v[64:67], v[0:7], v[216:223], v[64:67], v186, v186 op_sel_hi:[0,0,0]
	v_mfma_scale_f32_16x16x128_f8f6f4 v[56:59], v[8:15], v[216:223], v[56:59], v186, v186 op_sel_hi:[0,0,0]
	v_mfma_scale_f32_16x16x128_f8f6f4 v[48:51], v[0:7], v[224:231], v[48:51], v186, v186 op_sel_hi:[0,0,0]
	v_mfma_scale_f32_16x16x128_f8f6f4 v[40:43], v[8:15], v[224:231], v[40:43], v186, v186 op_sel_hi:[0,0,0]
	v_mfma_scale_f32_16x16x128_f8f6f4 v[84:87], v[16:23], v[194:201], v[84:87], v186, v186 op_sel_hi:[0,0,0]
	v_mfma_scale_f32_16x16x128_f8f6f4 v[76:79], v[24:31], v[194:201], v[76:79], v186, v186 op_sel_hi:[0,0,0]
	v_mfma_scale_f32_16x16x128_f8f6f4 v[68:71], v[16:23], v[208:215], v[68:71], v186, v186 op_sel_hi:[0,0,0]
	v_mfma_scale_f32_16x16x128_f8f6f4 v[60:63], v[24:31], v[208:215], v[60:63], v186, v186 op_sel_hi:[0,0,0]
	v_mfma_scale_f32_16x16x128_f8f6f4 v[52:55], v[16:23], v[216:223], v[52:55], v186, v186 op_sel_hi:[0,0,0]
	v_mfma_scale_f32_16x16x128_f8f6f4 v[44:47], v[24:31], v[216:223], v[44:47], v186, v186 op_sel_hi:[0,0,0]
	v_mfma_scale_f32_16x16x128_f8f6f4 v[36:39], v[16:23], v[224:231], v[36:39], v186, v186 op_sel_hi:[0,0,0]
	v_mfma_scale_f32_16x16x128_f8f6f4 v[32:35], v[24:31], v[224:231], v[32:35], v186, v186 op_sel_hi:[0,0,0]
	s_barrier
	s_setprio 0
	s_add_u32 s44, s44, 0x100
	s_addc_u32 s45, s45, 0
	s_add_i32 s70, s70, 2
	s_add_u32 s68, s68, 0x100
	s_addc_u32 s69, s69, 0
	s_cmp_gt_u32 s70, 29
	s_cbranch_scc0 .LBB0_705
	s_and_b64 vcc, exec, s[12:13]
	s_cbranch_vccz .LBB0_708
	s_barrier

.LBB0_1637:
	ds_read_b128 v[152:155], v149
	ds_read_b128 v[156:159], v149 offset:1024
	ds_read_b128 v[160:163], v149 offset:2048
	ds_read_b128 v[164:167], v149 offset:3072
	ds_read_b128 v[168:171], v150
	ds_read_b128 v[172:175], v150 offset:1024
	ds_read_b128 v[176:179], v150 offset:2048
	ds_read_b128 v[180:183], v150 offset:3072
	s_add_u32 s0, s42, 0xfff00080
	s_addc_u32 s1, s43, -1
	s_cmp_eq_u32 s68, 60
	s_cselect_b32 s47, s35, s1
	s_cselect_b32 s46, s64, s0
	s_cselect_b32 s45, s31, s67
	s_cselect_b32 s44, s65, s66
	s_add_i32 m0, s41, 0xc000
	ds_read_b128 v[184:187], v151
	ds_read_b128 v[188:191], v151 offset:1024
	ds_read_b128 v[192:195], v151 offset:2048
	ds_read_b128 v[196:199], v151 offset:3072
	ds_read_b128 v[200:203], v151 offset:4096
	ds_read_b128 v[210:213], v151 offset:5120
	ds_read_b128 v[214:217], v151 offset:6144
	global_load_lds_dwordx4 v136, s[42:43]
	s_add_i32 m0, s41, 0xe000
	ds_read_b128 v[218:221], v151 offset:7168
	global_load_lds_dwordx4 v138, s[42:43]
	s_waitcnt vmcnt(8) lgkmcnt(0)
	s_setprio 3
	s_barrier
	v_mfma_f32_16x16x32_bf16 v[124:127], v[152:155], v[184:187], v[124:127]
	v_mfma_f32_16x16x32_bf16 v[120:123], v[160:163], v[184:187], v[120:123]
	v_mfma_f32_16x16x32_bf16 v[116:119], v[152:155], v[192:195], v[116:119]
	v_mfma_f32_16x16x32_bf16 v[108:111], v[160:163], v[192:195], v[108:111]
	v_mfma_f32_16x16x32_bf16 v[100:103], v[152:155], v[200:203], v[100:103]
	v_mfma_f32_16x16x32_bf16 v[92:95], v[160:163], v[200:203], v[92:95]
	v_mfma_f32_16x16x32_bf16 v[84:87], v[152:155], v[214:217], v[84:87]
	v_mfma_f32_16x16x32_bf16 v[76:79], v[160:163], v[214:217], v[76:79]
	v_mfma_f32_16x16x32_bf16 v[124:127], v[156:159], v[188:191], v[124:127]
	v_mfma_f32_16x16x32_bf16 v[120:123], v[164:167], v[188:191], v[120:123]
	v_mfma_f32_16x16x32_bf16 v[116:119], v[156:159], v[196:199], v[116:119]
	v_mfma_f32_16x16x32_bf16 v[108:111], v[164:167], v[196:199], v[108:111]
	v_mfma_f32_16x16x32_bf16 v[100:103], v[156:159], v[210:213], v[100:103]
	v_mfma_f32_16x16x32_bf16 v[92:95], v[164:167], v[210:213], v[92:95]
	v_mfma_f32_16x16x32_bf16 v[84:87], v[156:159], v[218:221], v[84:87]
	v_mfma_f32_16x16x32_bf16 v[76:79], v[164:167], v[218:221], v[76:79]
	v_mfma_f32_16x16x32_bf16 v[112:115], v[168:171], v[184:187], v[112:115]
	v_mfma_f32_16x16x32_bf16 v[104:107], v[176:179], v[184:187], v[104:107]
	v_mfma_f32_16x16x32_bf16 v[96:99], v[168:171], v[192:195], v[96:99]
	v_mfma_f32_16x16x32_bf16 v[88:91], v[176:179], v[192:195], v[88:91]
	v_mfma_f32_16x16x32_bf16 v[80:83], v[168:171], v[200:203], v[80:83]
	v_mfma_f32_16x16x32_bf16 v[72:75], v[176:179], v[200:203], v[72:75]
	v_mfma_f32_16x16x32_bf16 v[68:71], v[168:171], v[214:217], v[68:71]
	v_mfma_f32_16x16x32_bf16 v[64:67], v[176:179], v[214:217], v[64:67]
	v_mfma_f32_16x16x32_bf16 v[112:115], v[172:175], v[188:191], v[112:115]
	v_mfma_f32_16x16x32_bf16 v[104:107], v[180:183], v[188:191], v[104:107]
	v_mfma_f32_16x16x32_bf16 v[96:99], v[172:175], v[196:199], v[96:99]
	v_mfma_f32_16x16x32_bf16 v[88:91], v[180:183], v[196:199], v[88:91]
	v_mfma_f32_16x16x32_bf16 v[80:83], v[172:175], v[210:213], v[80:83]
	v_mfma_f32_16x16x32_bf16 v[72:75], v[180:183], v[210:213], v[72:75]
	v_mfma_f32_16x16x32_bf16 v[68:71], v[172:175], v[218:221], v[68:71]
	v_mfma_f32_16x16x32_bf16 v[64:67], v[180:183], v[218:221], v[64:67]
	s_barrier
	s_setprio 0
	s_add_i32 m0, s57, s49
	ds_read_b128 v[184:187], v151 offset:16384
	ds_read_b128 v[188:191], v151 offset:17408
	ds_read_b128 v[192:195], v151 offset:18432
	ds_read_b128 v[196:199], v151 offset:19456
	ds_read_b128 v[200:203], v151 offset:20480
	global_load_lds_dwordx4 v130, s[44:45]
	s_add_i32 m0, m0, 0x2000
	s_add_u32 s0, s44, 0x100000
	s_addc_u32 s1, s45, 0
	s_add_i32 s69, s58, s49
	global_load_lds_dwordx4 v134, s[44:45]
	s_mov_b32 m0, s69
	s_nop 0
	global_load_lds_dwordx4 v130, s[0:1]
	s_add_i32 m0, s69, 0x2000
	ds_read_b128 v[218:221], v151 offset:23552
	global_load_lds_dwordx4 v134, s[0:1]
	s_mov_b32 m0, s41
	ds_read_b128 v[214:217], v151 offset:22528
	global_load_lds_dwordx4 v128, s[46:47]
	s_mov_b32 m0, s50
	ds_read_b128 v[210:213], v151 offset:21504
	global_load_lds_dwordx4 v132, s[46:47]
	s_waitcnt vmcnt(8) lgkmcnt(0)
	s_setprio 3
	s_barrier
	v_mfma_f32_16x16x32_bf16 v[60:63], v[152:155], v[184:187], v[60:63]
	v_mfma_f32_16x16x32_bf16 v[56:59], v[160:163], v[184:187], v[56:59]
	v_mfma_f32_16x16x32_bf16 v[52:55], v[152:155], v[192:195], v[52:55]
	v_mfma_f32_16x16x32_bf16 v[44:47], v[160:163], v[192:195], v[44:47]
	v_mfma_f32_16x16x32_bf16 v[36:39], v[152:155], v[200:203], v[36:39]
	v_mfma_f32_16x16x32_bf16 v[28:31], v[160:163], v[200:203], v[28:31]
	v_mfma_f32_16x16x32_bf16 v[20:23], v[152:155], v[214:217], v[20:23]
	v_mfma_f32_16x16x32_bf16 v[12:15], v[160:163], v[214:217], v[12:15]
	v_mfma_f32_16x16x32_bf16 v[60:63], v[156:159], v[188:191], v[60:63]
	v_mfma_f32_16x16x32_bf16 v[56:59], v[164:167], v[188:191], v[56:59]
	v_mfma_f32_16x16x32_bf16 v[52:55], v[156:159], v[196:199], v[52:55]
	v_mfma_f32_16x16x32_bf16 v[44:47], v[164:167], v[196:199], v[44:47]
	v_mfma_f32_16x16x32_bf16 v[36:39], v[156:159], v[210:213], v[36:39]
	v_mfma_f32_16x16x32_bf16 v[28:31], v[164:167], v[210:213], v[28:31]
	v_mfma_f32_16x16x32_bf16 v[20:23], v[156:159], v[218:221], v[20:23]
	v_mfma_f32_16x16x32_bf16 v[12:15], v[164:167], v[218:221], v[12:15]
	v_mfma_f32_16x16x32_bf16 v[48:51], v[168:171], v[184:187], v[48:51]
	v_mfma_f32_16x16x32_bf16 v[40:43], v[176:179], v[184:187], v[40:43]
	v_mfma_f32_16x16x32_bf16 v[32:35], v[168:171], v[192:195], v[32:35]
	v_mfma_f32_16x16x32_bf16 v[24:27], v[176:179], v[192:195], v[24:27]
	v_mfma_f32_16x16x32_bf16 v[16:19], v[168:171], v[200:203], v[16:19]
	v_mfma_f32_16x16x32_bf16 v[8:11], v[176:179], v[200:203], v[8:11]
	v_mfma_f32_16x16x32_bf16 v[4:7], v[168:171], v[214:217], v[4:7]
	v_mfma_f32_16x16x32_bf16 v[0:3], v[176:179], v[214:217], v[0:3]
	v_mfma_f32_16x16x32_bf16 v[48:51], v[172:175], v[188:191], v[48:51]
	v_mfma_f32_16x16x32_bf16 v[40:43], v[180:183], v[188:191], v[40:43]
	v_mfma_f32_16x16x32_bf16 v[32:35], v[172:175], v[196:199], v[32:35]
	v_mfma_f32_16x16x32_bf16 v[24:27], v[180:183], v[196:199], v[24:27]
	v_mfma_f32_16x16x32_bf16 v[16:19], v[172:175], v[210:213], v[16:19]
	v_mfma_f32_16x16x32_bf16 v[8:11], v[180:183], v[210:213], v[8:11]
	v_mfma_f32_16x16x32_bf16 v[4:7], v[172:175], v[218:221], v[4:7]
	v_mfma_f32_16x16x32_bf16 v[0:3], v[180:183], v[218:221], v[0:3]
	s_barrier
	s_setprio 0
	s_add_i32 s69, 0, 0x18000
	s_add_i32 s70, 0, 0x1c000
	ds_read_b128 v[152:155], v228
	ds_read_b128 v[156:159], v228 offset:1024
	ds_read_b128 v[160:163], v228 offset:2048
	ds_read_b128 v[164:167], v228 offset:3072
	ds_read_b128 v[168:171], v229
	ds_read_b128 v[172:175], v229 offset:1024
	ds_read_b128 v[176:179], v229 offset:2048
	ds_read_b128 v[180:183], v229 offset:3072
	s_add_u32 s0, s46, 0x100000
	s_addc_u32 s1, s47, 0
	s_mov_b32 m0, s51
	ds_read_b128 v[184:187], v151 offset:32768
	ds_read_b128 v[188:191], v151 offset:33792
	ds_read_b128 v[192:195], v151 offset:34816
	ds_read_b128 v[196:199], v151 offset:35840
	ds_read_b128 v[200:203], v151 offset:36864
	ds_read_b128 v[210:213], v151 offset:37888
	ds_read_b128 v[214:217], v151 offset:38912
	global_load_lds_dwordx4 v128, s[0:1]
	s_mov_b32 m0, s52
	ds_read_b128 v[218:221], v151 offset:39936
	global_load_lds_dwordx4 v132, s[0:1]
	s_waitcnt vmcnt(8) lgkmcnt(0)
	s_setprio 3
	s_barrier
	v_mfma_f32_16x16x32_bf16 v[124:127], v[152:155], v[184:187], v[124:127]
	v_mfma_f32_16x16x32_bf16 v[120:123], v[160:163], v[184:187], v[120:123]
	v_mfma_f32_16x16x32_bf16 v[116:119], v[152:155], v[192:195], v[116:119]
	v_mfma_f32_16x16x32_bf16 v[108:111], v[160:163], v[192:195], v[108:111]
	v_mfma_f32_16x16x32_bf16 v[100:103], v[152:155], v[200:203], v[100:103]
	v_mfma_f32_16x16x32_bf16 v[92:95], v[160:163], v[200:203], v[92:95]
	v_mfma_f32_16x16x32_bf16 v[84:87], v[152:155], v[214:217], v[84:87]
	v_mfma_f32_16x16x32_bf16 v[76:79], v[160:163], v[214:217], v[76:79]
	v_mfma_f32_16x16x32_bf16 v[124:127], v[156:159], v[188:191], v[124:127]
	v_mfma_f32_16x16x32_bf16 v[120:123], v[164:167], v[188:191], v[120:123]
	v_mfma_f32_16x16x32_bf16 v[116:119], v[156:159], v[196:199], v[116:119]
	v_mfma_f32_16x16x32_bf16 v[108:111], v[164:167], v[196:199], v[108:111]
	v_mfma_f32_16x16x32_bf16 v[100:103], v[156:159], v[210:213], v[100:103]
	v_mfma_f32_16x16x32_bf16 v[92:95], v[164:167], v[210:213], v[92:95]
	v_mfma_f32_16x16x32_bf16 v[84:87], v[156:159], v[218:221], v[84:87]
	v_mfma_f32_16x16x32_bf16 v[76:79], v[164:167], v[218:221], v[76:79]
	v_mfma_f32_16x16x32_bf16 v[112:115], v[168:171], v[184:187], v[112:115]
	v_mfma_f32_16x16x32_bf16 v[104:107], v[176:179], v[184:187], v[104:107]
	v_mfma_f32_16x16x32_bf16 v[96:99], v[168:171], v[192:195], v[96:99]
	v_mfma_f32_16x16x32_bf16 v[88:91], v[176:179], v[192:195], v[88:91]
	v_mfma_f32_16x16x32_bf16 v[80:83], v[168:171], v[200:203], v[80:83]
	v_mfma_f32_16x16x32_bf16 v[72:75], v[176:179], v[200:203], v[72:75]
	v_mfma_f32_16x16x32_bf16 v[68:71], v[168:171], v[214:217], v[68:71]
	v_mfma_f32_16x16x32_bf16 v[64:67], v[176:179], v[214:217], v[64:67]
	v_mfma_f32_16x16x32_bf16 v[112:115], v[172:175], v[188:191], v[112:115]
	v_mfma_f32_16x16x32_bf16 v[104:107], v[180:183], v[188:191], v[104:107]
	v_mfma_f32_16x16x32_bf16 v[96:99], v[172:175], v[196:199], v[96:99]
	v_mfma_f32_16x16x32_bf16 v[88:91], v[180:183], v[196:199], v[88:91]
	v_mfma_f32_16x16x32_bf16 v[80:83], v[172:175], v[210:213], v[80:83]
	v_mfma_f32_16x16x32_bf16 v[72:75], v[180:183], v[210:213], v[72:75]
	v_mfma_f32_16x16x32_bf16 v[68:71], v[172:175], v[218:221], v[68:71]
	v_mfma_f32_16x16x32_bf16 v[64:67], v[180:183], v[218:221], v[64:67]
	s_barrier
	s_setprio 0
	s_add_u32 s100, s44, 0x80
	s_addc_u32 s101, s45, 0
	s_add_i32 m0, s69, s49
	ds_read_b128 v[184:187], v151 offset:49152
	ds_read_b128 v[188:191], v151 offset:50176
	ds_read_b128 v[192:195], v151 offset:51200
	ds_read_b128 v[196:199], v151 offset:52224
	global_load_lds_dwordx4 v130, s[100:101]
	s_add_i32 m0, m0, 0x2000
	s_add_u32 s0, s44, 0x100080
	s_addc_u32 s1, s45, 0
	s_add_i32 s44, s70, s49
	global_load_lds_dwordx4 v134, s[100:101]
	s_mov_b32 m0, s44
	ds_read_b128 v[218:221], v151 offset:56320
	global_load_lds_dwordx4 v130, s[0:1]
	s_add_i32 m0, s44, 0x2000
	ds_read_b128 v[214:217], v151 offset:55296
	global_load_lds_dwordx4 v134, s[0:1]
	s_add_u32 s100, s46, 0x80
	s_addc_u32 s101, s47, 0
	s_mov_b32 m0, s54
	ds_read_b128 v[210:213], v151 offset:54272
	global_load_lds_dwordx4 v128, s[100:101]
	s_mov_b32 m0, s55
	ds_read_b128 v[200:203], v151 offset:53248
	global_load_lds_dwordx4 v132, s[100:101]
	s_waitcnt vmcnt(8) lgkmcnt(0)
	s_setprio 3
	s_barrier
	v_mfma_f32_16x16x32_bf16 v[60:63], v[152:155], v[184:187], v[60:63]
	v_mfma_f32_16x16x32_bf16 v[56:59], v[160:163], v[184:187], v[56:59]
	v_mfma_f32_16x16x32_bf16 v[52:55], v[152:155], v[192:195], v[52:55]
	v_mfma_f32_16x16x32_bf16 v[44:47], v[160:163], v[192:195], v[44:47]
	v_mfma_f32_16x16x32_bf16 v[36:39], v[152:155], v[200:203], v[36:39]
	v_mfma_f32_16x16x32_bf16 v[28:31], v[160:163], v[200:203], v[28:31]
	v_mfma_f32_16x16x32_bf16 v[20:23], v[152:155], v[214:217], v[20:23]
	v_mfma_f32_16x16x32_bf16 v[12:15], v[160:163], v[214:217], v[12:15]
	v_mfma_f32_16x16x32_bf16 v[60:63], v[156:159], v[188:191], v[60:63]
	v_mfma_f32_16x16x32_bf16 v[56:59], v[164:167], v[188:191], v[56:59]
	v_mfma_f32_16x16x32_bf16 v[52:55], v[156:159], v[196:199], v[52:55]
	v_mfma_f32_16x16x32_bf16 v[44:47], v[164:167], v[196:199], v[44:47]
	v_mfma_f32_16x16x32_bf16 v[36:39], v[156:159], v[210:213], v[36:39]
	v_mfma_f32_16x16x32_bf16 v[28:31], v[164:167], v[210:213], v[28:31]
	v_mfma_f32_16x16x32_bf16 v[20:23], v[156:159], v[218:221], v[20:23]
	v_mfma_f32_16x16x32_bf16 v[12:15], v[164:167], v[218:221], v[12:15]
	v_mfma_f32_16x16x32_bf16 v[48:51], v[168:171], v[184:187], v[48:51]
	v_mfma_f32_16x16x32_bf16 v[40:43], v[176:179], v[184:187], v[40:43]
	v_mfma_f32_16x16x32_bf16 v[32:35], v[168:171], v[192:195], v[32:35]
	v_mfma_f32_16x16x32_bf16 v[24:27], v[176:179], v[192:195], v[24:27]
	v_mfma_f32_16x16x32_bf16 v[16:19], v[168:171], v[200:203], v[16:19]
	v_mfma_f32_16x16x32_bf16 v[8:11], v[176:179], v[200:203], v[8:11]
	v_mfma_f32_16x16x32_bf16 v[4:7], v[168:171], v[214:217], v[4:7]
	v_mfma_f32_16x16x32_bf16 v[0:3], v[176:179], v[214:217], v[0:3]
	v_mfma_f32_16x16x32_bf16 v[48:51], v[172:175], v[188:191], v[48:51]
	v_mfma_f32_16x16x32_bf16 v[40:43], v[180:183], v[188:191], v[40:43]
	v_mfma_f32_16x16x32_bf16 v[32:35], v[172:175], v[196:199], v[32:35]
	v_mfma_f32_16x16x32_bf16 v[24:27], v[180:183], v[196:199], v[24:27]
	v_mfma_f32_16x16x32_bf16 v[16:19], v[172:175], v[210:213], v[16:19]
	v_mfma_f32_16x16x32_bf16 v[8:11], v[180:183], v[210:213], v[8:11]
	v_mfma_f32_16x16x32_bf16 v[4:7], v[172:175], v[218:221], v[4:7]
	v_mfma_f32_16x16x32_bf16 v[0:3], v[180:183], v[218:221], v[0:3]
	s_barrier
	s_setprio 0
	s_add_u32 s42, s42, 0x100
	s_addc_u32 s43, s43, 0
	s_add_i32 s68, s68, 2
	s_add_u32 s66, s66, 0x100
	s_addc_u32 s67, s67, 0
	s_cmp_gt_u32 s68, 61
	s_cbranch_scc0 .LBB0_1637
	s_and_b64 vcc, exec, s[16:17]
	s_cbranch_vccz .LBB0_1640
	s_barrier

.LBB0_1813:
	ds_read_b128 v[148:151], v156
	ds_read_b128 v[160:163], v156 offset:1024
	ds_read_b128 v[164:167], v156 offset:2048
	ds_read_b128 v[168:171], v156 offset:3072
	ds_read_b128 v[172:175], v157
	ds_read_b128 v[176:179], v157 offset:1024
	ds_read_b128 v[180:183], v157 offset:2048
	ds_read_b128 v[184:187], v157 offset:3072
	s_add_u32 s0, s36, 0xfff00080
	s_addc_u32 s1, s37, -1
	s_cmp_eq_u32 s64, 60
	s_cselect_b32 s41, s59, s1
	s_cselect_b32 s40, s60, s0
	s_cselect_b32 s39, s17, s63
	s_cselect_b32 s38, s61, s62
	s_add_i32 m0, s31, 0xc000
	ds_read_b128 v[188:191], v158
	ds_read_b128 v[192:195], v158 offset:1024
	ds_read_b128 v[196:199], v158 offset:2048
	ds_read_b128 v[200:203], v158 offset:3072
	ds_read_b128 v[210:213], v158 offset:4096
	ds_read_b128 v[214:217], v158 offset:5120
	ds_read_b128 v[218:221], v158 offset:6144
	global_load_lds_dwordx4 v140, s[36:37]
	s_add_i32 m0, s31, 0xe000
	ds_read_b128 v[222:225], v158 offset:7168
	global_load_lds_dwordx4 v142, s[36:37]
	s_waitcnt vmcnt(8) lgkmcnt(0)
	s_setprio 3
	s_barrier
	v_mfma_f32_16x16x32_bf16 v[124:127], v[148:151], v[188:191], v[124:127]
	v_mfma_f32_16x16x32_bf16 v[120:123], v[164:167], v[188:191], v[120:123]
	v_mfma_f32_16x16x32_bf16 v[108:111], v[148:151], v[196:199], v[108:111]
	v_mfma_f32_16x16x32_bf16 v[104:107], v[164:167], v[196:199], v[104:107]
	v_mfma_f32_16x16x32_bf16 v[92:95], v[148:151], v[210:213], v[92:95]
	v_mfma_f32_16x16x32_bf16 v[88:91], v[164:167], v[210:213], v[88:91]
	v_mfma_f32_16x16x32_bf16 v[76:79], v[148:151], v[218:221], v[76:79]
	v_mfma_f32_16x16x32_bf16 v[72:75], v[164:167], v[218:221], v[72:75]
	v_mfma_f32_16x16x32_bf16 v[124:127], v[160:163], v[192:195], v[124:127]
	v_mfma_f32_16x16x32_bf16 v[120:123], v[168:171], v[192:195], v[120:123]
	v_mfma_f32_16x16x32_bf16 v[108:111], v[160:163], v[200:203], v[108:111]
	v_mfma_f32_16x16x32_bf16 v[104:107], v[168:171], v[200:203], v[104:107]
	v_mfma_f32_16x16x32_bf16 v[92:95], v[160:163], v[214:217], v[92:95]
	v_mfma_f32_16x16x32_bf16 v[88:91], v[168:171], v[214:217], v[88:91]
	v_mfma_f32_16x16x32_bf16 v[76:79], v[160:163], v[222:225], v[76:79]
	v_mfma_f32_16x16x32_bf16 v[72:75], v[168:171], v[222:225], v[72:75]
	v_mfma_f32_16x16x32_bf16 v[116:119], v[172:175], v[188:191], v[116:119]
	v_mfma_f32_16x16x32_bf16 v[112:115], v[180:183], v[188:191], v[112:115]
	v_mfma_f32_16x16x32_bf16 v[100:103], v[172:175], v[196:199], v[100:103]
	v_mfma_f32_16x16x32_bf16 v[96:99], v[180:183], v[196:199], v[96:99]
	v_mfma_f32_16x16x32_bf16 v[84:87], v[172:175], v[210:213], v[84:87]
	v_mfma_f32_16x16x32_bf16 v[80:83], v[180:183], v[210:213], v[80:83]
	v_mfma_f32_16x16x32_bf16 v[68:71], v[172:175], v[218:221], v[68:71]
	v_mfma_f32_16x16x32_bf16 v[64:67], v[180:183], v[218:221], v[64:67]
	v_mfma_f32_16x16x32_bf16 v[116:119], v[176:179], v[192:195], v[116:119]
	v_mfma_f32_16x16x32_bf16 v[112:115], v[184:187], v[192:195], v[112:115]
	v_mfma_f32_16x16x32_bf16 v[100:103], v[176:179], v[200:203], v[100:103]
	v_mfma_f32_16x16x32_bf16 v[96:99], v[184:187], v[200:203], v[96:99]
	v_mfma_f32_16x16x32_bf16 v[84:87], v[176:179], v[214:217], v[84:87]
	v_mfma_f32_16x16x32_bf16 v[80:83], v[184:187], v[214:217], v[80:83]
	v_mfma_f32_16x16x32_bf16 v[68:71], v[176:179], v[222:225], v[68:71]
	v_mfma_f32_16x16x32_bf16 v[64:67], v[184:187], v[222:225], v[64:67]
	s_barrier
	s_setprio 0
	s_add_i32 m0, s52, s43
	ds_read_b128 v[188:191], v158 offset:16384
	ds_read_b128 v[192:195], v158 offset:17408
	ds_read_b128 v[196:199], v158 offset:18432
	ds_read_b128 v[200:203], v158 offset:19456
	ds_read_b128 v[210:213], v158 offset:20480
	global_load_lds_dwordx4 v132, s[38:39]
	s_add_i32 m0, m0, 0x2000
	s_add_u32 s0, s38, 0x100000
	s_addc_u32 s1, s39, 0
	s_add_i32 s65, s53, s43
	global_load_lds_dwordx4 v136, s[38:39]
	s_mov_b32 m0, s65
	s_nop 0
	global_load_lds_dwordx4 v132, s[0:1]
	s_add_i32 m0, s65, 0x2000
	ds_read_b128 v[222:225], v158 offset:23552
	global_load_lds_dwordx4 v136, s[0:1]
	s_mov_b32 m0, s31
	ds_read_b128 v[218:221], v158 offset:22528
	global_load_lds_dwordx4 v130, s[40:41]
	s_mov_b32 m0, s35
	ds_read_b128 v[214:217], v158 offset:21504
	global_load_lds_dwordx4 v134, s[40:41]
	s_waitcnt vmcnt(8) lgkmcnt(0)
	s_setprio 3
	s_barrier
	v_mfma_f32_16x16x32_bf16 v[60:63], v[148:151], v[188:191], v[60:63]
	v_mfma_f32_16x16x32_bf16 v[56:59], v[164:167], v[188:191], v[56:59]
	v_mfma_f32_16x16x32_bf16 v[44:47], v[148:151], v[196:199], v[44:47]
	v_mfma_f32_16x16x32_bf16 v[40:43], v[164:167], v[196:199], v[40:43]
	v_mfma_f32_16x16x32_bf16 v[28:31], v[148:151], v[210:213], v[28:31]
	v_mfma_f32_16x16x32_bf16 v[24:27], v[164:167], v[210:213], v[24:27]
	v_mfma_f32_16x16x32_bf16 v[12:15], v[148:151], v[218:221], v[12:15]
	v_mfma_f32_16x16x32_bf16 v[8:11], v[164:167], v[218:221], v[8:11]
	v_mfma_f32_16x16x32_bf16 v[60:63], v[160:163], v[192:195], v[60:63]
	v_mfma_f32_16x16x32_bf16 v[56:59], v[168:171], v[192:195], v[56:59]
	v_mfma_f32_16x16x32_bf16 v[44:47], v[160:163], v[200:203], v[44:47]
	v_mfma_f32_16x16x32_bf16 v[40:43], v[168:171], v[200:203], v[40:43]
	v_mfma_f32_16x16x32_bf16 v[28:31], v[160:163], v[214:217], v[28:31]
	v_mfma_f32_16x16x32_bf16 v[24:27], v[168:171], v[214:217], v[24:27]
	v_mfma_f32_16x16x32_bf16 v[12:15], v[160:163], v[222:225], v[12:15]
	v_mfma_f32_16x16x32_bf16 v[8:11], v[168:171], v[222:225], v[8:11]
	v_mfma_f32_16x16x32_bf16 v[52:55], v[172:175], v[188:191], v[52:55]
	v_mfma_f32_16x16x32_bf16 v[48:51], v[180:183], v[188:191], v[48:51]
	v_mfma_f32_16x16x32_bf16 v[36:39], v[172:175], v[196:199], v[36:39]
	v_mfma_f32_16x16x32_bf16 v[32:35], v[180:183], v[196:199], v[32:35]
	v_mfma_f32_16x16x32_bf16 v[20:23], v[172:175], v[210:213], v[20:23]
	v_mfma_f32_16x16x32_bf16 v[16:19], v[180:183], v[210:213], v[16:19]
	v_mfma_f32_16x16x32_bf16 v[4:7], v[172:175], v[218:221], v[4:7]
	v_mfma_f32_16x16x32_bf16 v[0:3], v[180:183], v[218:221], v[0:3]
	v_mfma_f32_16x16x32_bf16 v[52:55], v[176:179], v[192:195], v[52:55]
	v_mfma_f32_16x16x32_bf16 v[48:51], v[184:187], v[192:195], v[48:51]
	v_mfma_f32_16x16x32_bf16 v[36:39], v[176:179], v[200:203], v[36:39]
	v_mfma_f32_16x16x32_bf16 v[32:35], v[184:187], v[200:203], v[32:35]
	v_mfma_f32_16x16x32_bf16 v[20:23], v[176:179], v[214:217], v[20:23]
	v_mfma_f32_16x16x32_bf16 v[16:19], v[184:187], v[214:217], v[16:19]
	v_mfma_f32_16x16x32_bf16 v[4:7], v[176:179], v[222:225], v[4:7]
	v_mfma_f32_16x16x32_bf16 v[0:3], v[184:187], v[222:225], v[0:3]
	s_barrier
	s_setprio 0
	s_add_i32 s65, 0, 0x18000
	s_add_i32 s66, 0, 0x1c000
	ds_read_b128 v[148:151], v234
	ds_read_b128 v[160:163], v234 offset:1024
	ds_read_b128 v[164:167], v234 offset:2048
	ds_read_b128 v[168:171], v234 offset:3072
	ds_read_b128 v[172:175], v235
	ds_read_b128 v[176:179], v235 offset:1024
	ds_read_b128 v[180:183], v235 offset:2048
	ds_read_b128 v[184:187], v235 offset:3072
	s_add_u32 s0, s40, 0x100000
	s_addc_u32 s1, s41, 0
	s_mov_b32 m0, s44
	ds_read_b128 v[188:191], v158 offset:32768
	ds_read_b128 v[192:195], v158 offset:33792
	ds_read_b128 v[196:199], v158 offset:34816
	ds_read_b128 v[200:203], v158 offset:35840
	ds_read_b128 v[210:213], v158 offset:36864
	ds_read_b128 v[214:217], v158 offset:37888
	ds_read_b128 v[218:221], v158 offset:38912
	global_load_lds_dwordx4 v130, s[0:1]
	s_mov_b32 m0, s45
	ds_read_b128 v[222:225], v158 offset:39936
	global_load_lds_dwordx4 v134, s[0:1]
	s_waitcnt vmcnt(8) lgkmcnt(0)
	s_setprio 3
	s_barrier
	v_mfma_f32_16x16x32_bf16 v[124:127], v[148:151], v[188:191], v[124:127]
	v_mfma_f32_16x16x32_bf16 v[120:123], v[164:167], v[188:191], v[120:123]
	v_mfma_f32_16x16x32_bf16 v[108:111], v[148:151], v[196:199], v[108:111]
	v_mfma_f32_16x16x32_bf16 v[104:107], v[164:167], v[196:199], v[104:107]
	v_mfma_f32_16x16x32_bf16 v[92:95], v[148:151], v[210:213], v[92:95]
	v_mfma_f32_16x16x32_bf16 v[88:91], v[164:167], v[210:213], v[88:91]
	v_mfma_f32_16x16x32_bf16 v[76:79], v[148:151], v[218:221], v[76:79]
	v_mfma_f32_16x16x32_bf16 v[72:75], v[164:167], v[218:221], v[72:75]
	v_mfma_f32_16x16x32_bf16 v[124:127], v[160:163], v[192:195], v[124:127]
	v_mfma_f32_16x16x32_bf16 v[120:123], v[168:171], v[192:195], v[120:123]
	v_mfma_f32_16x16x32_bf16 v[108:111], v[160:163], v[200:203], v[108:111]
	v_mfma_f32_16x16x32_bf16 v[104:107], v[168:171], v[200:203], v[104:107]
	v_mfma_f32_16x16x32_bf16 v[92:95], v[160:163], v[214:217], v[92:95]
	v_mfma_f32_16x16x32_bf16 v[88:91], v[168:171], v[214:217], v[88:91]
	v_mfma_f32_16x16x32_bf16 v[76:79], v[160:163], v[222:225], v[76:79]
	v_mfma_f32_16x16x32_bf16 v[72:75], v[168:171], v[222:225], v[72:75]
	v_mfma_f32_16x16x32_bf16 v[116:119], v[172:175], v[188:191], v[116:119]
	v_mfma_f32_16x16x32_bf16 v[112:115], v[180:183], v[188:191], v[112:115]
	v_mfma_f32_16x16x32_bf16 v[100:103], v[172:175], v[196:199], v[100:103]
	v_mfma_f32_16x16x32_bf16 v[96:99], v[180:183], v[196:199], v[96:99]
	v_mfma_f32_16x16x32_bf16 v[84:87], v[172:175], v[210:213], v[84:87]
	v_mfma_f32_16x16x32_bf16 v[80:83], v[180:183], v[210:213], v[80:83]
	v_mfma_f32_16x16x32_bf16 v[68:71], v[172:175], v[218:221], v[68:71]
	v_mfma_f32_16x16x32_bf16 v[64:67], v[180:183], v[218:221], v[64:67]
	v_mfma_f32_16x16x32_bf16 v[116:119], v[176:179], v[192:195], v[116:119]
	v_mfma_f32_16x16x32_bf16 v[112:115], v[184:187], v[192:195], v[112:115]
	v_mfma_f32_16x16x32_bf16 v[100:103], v[176:179], v[200:203], v[100:103]
	v_mfma_f32_16x16x32_bf16 v[96:99], v[184:187], v[200:203], v[96:99]
	v_mfma_f32_16x16x32_bf16 v[84:87], v[176:179], v[214:217], v[84:87]
	v_mfma_f32_16x16x32_bf16 v[80:83], v[184:187], v[214:217], v[80:83]
	v_mfma_f32_16x16x32_bf16 v[68:71], v[176:179], v[222:225], v[68:71]
	v_mfma_f32_16x16x32_bf16 v[64:67], v[184:187], v[222:225], v[64:67]
	s_barrier
	s_setprio 0
	s_add_u32 s100, s38, 0x80
	s_addc_u32 s101, s39, 0
	s_add_i32 m0, s65, s43
	ds_read_b128 v[188:191], v158 offset:49152
	ds_read_b128 v[192:195], v158 offset:50176
	ds_read_b128 v[196:199], v158 offset:51200
	ds_read_b128 v[200:203], v158 offset:52224
	global_load_lds_dwordx4 v132, s[100:101]
	s_add_i32 m0, m0, 0x2000
	s_add_u32 s0, s38, 0x100080
	s_addc_u32 s1, s39, 0
	s_add_i32 s38, s66, s43
	global_load_lds_dwordx4 v136, s[100:101]
	s_mov_b32 m0, s38
	ds_read_b128 v[222:225], v158 offset:56320
	global_load_lds_dwordx4 v132, s[0:1]
	s_add_i32 m0, s38, 0x2000
	ds_read_b128 v[218:221], v158 offset:55296
	global_load_lds_dwordx4 v136, s[0:1]
	s_add_u32 s100, s40, 0x80
	s_addc_u32 s101, s41, 0
	s_mov_b32 m0, s49
	ds_read_b128 v[214:217], v158 offset:54272
	global_load_lds_dwordx4 v130, s[100:101]
	s_mov_b32 m0, s50
	ds_read_b128 v[210:213], v158 offset:53248
	global_load_lds_dwordx4 v134, s[100:101]
	s_waitcnt vmcnt(8) lgkmcnt(0)
	s_setprio 3
	s_barrier
	v_mfma_f32_16x16x32_bf16 v[60:63], v[148:151], v[188:191], v[60:63]
	v_mfma_f32_16x16x32_bf16 v[56:59], v[164:167], v[188:191], v[56:59]
	v_mfma_f32_16x16x32_bf16 v[44:47], v[148:151], v[196:199], v[44:47]
	v_mfma_f32_16x16x32_bf16 v[40:43], v[164:167], v[196:199], v[40:43]
	v_mfma_f32_16x16x32_bf16 v[28:31], v[148:151], v[210:213], v[28:31]
	v_mfma_f32_16x16x32_bf16 v[24:27], v[164:167], v[210:213], v[24:27]
	v_mfma_f32_16x16x32_bf16 v[12:15], v[148:151], v[218:221], v[12:15]
	v_mfma_f32_16x16x32_bf16 v[8:11], v[164:167], v[218:221], v[8:11]
	v_mfma_f32_16x16x32_bf16 v[60:63], v[160:163], v[192:195], v[60:63]
	v_mfma_f32_16x16x32_bf16 v[56:59], v[168:171], v[192:195], v[56:59]
	v_mfma_f32_16x16x32_bf16 v[44:47], v[160:163], v[200:203], v[44:47]
	v_mfma_f32_16x16x32_bf16 v[40:43], v[168:171], v[200:203], v[40:43]
	v_mfma_f32_16x16x32_bf16 v[28:31], v[160:163], v[214:217], v[28:31]
	v_mfma_f32_16x16x32_bf16 v[24:27], v[168:171], v[214:217], v[24:27]
	v_mfma_f32_16x16x32_bf16 v[12:15], v[160:163], v[222:225], v[12:15]
	v_mfma_f32_16x16x32_bf16 v[8:11], v[168:171], v[222:225], v[8:11]
	v_mfma_f32_16x16x32_bf16 v[52:55], v[172:175], v[188:191], v[52:55]
	v_mfma_f32_16x16x32_bf16 v[48:51], v[180:183], v[188:191], v[48:51]
	v_mfma_f32_16x16x32_bf16 v[36:39], v[172:175], v[196:199], v[36:39]
	v_mfma_f32_16x16x32_bf16 v[32:35], v[180:183], v[196:199], v[32:35]
	v_mfma_f32_16x16x32_bf16 v[20:23], v[172:175], v[210:213], v[20:23]
	v_mfma_f32_16x16x32_bf16 v[16:19], v[180:183], v[210:213], v[16:19]
	v_mfma_f32_16x16x32_bf16 v[4:7], v[172:175], v[218:221], v[4:7]
	v_mfma_f32_16x16x32_bf16 v[0:3], v[180:183], v[218:221], v[0:3]
	v_mfma_f32_16x16x32_bf16 v[52:55], v[176:179], v[192:195], v[52:55]
	v_mfma_f32_16x16x32_bf16 v[48:51], v[184:187], v[192:195], v[48:51]
	v_mfma_f32_16x16x32_bf16 v[36:39], v[176:179], v[200:203], v[36:39]
	v_mfma_f32_16x16x32_bf16 v[32:35], v[184:187], v[200:203], v[32:35]
	v_mfma_f32_16x16x32_bf16 v[20:23], v[176:179], v[214:217], v[20:23]
	v_mfma_f32_16x16x32_bf16 v[16:19], v[184:187], v[214:217], v[16:19]
	v_mfma_f32_16x16x32_bf16 v[4:7], v[176:179], v[222:225], v[4:7]
	v_mfma_f32_16x16x32_bf16 v[0:3], v[184:187], v[222:225], v[0:3]
	s_barrier
	s_setprio 0
	s_add_u32 s36, s36, 0x100
	s_addc_u32 s37, s37, 0
	s_add_i32 s64, s64, 2
	s_add_u32 s62, s62, 0x100
	s_addc_u32 s63, s63, 0
	s_cmp_gt_u32 s64, 61
	s_cbranch_scc0 .LBB0_1813
	s_and_b64 vcc, exec, s[14:15]
	s_cbranch_vccz .LBB0_1816
	s_barrier

.LBB0_1833:
	ds_read_b128 v[24:27], v193
	ds_read_b128 v[28:31], v193 offset:1024
	ds_read_b128 v[16:19], v193 offset:2048
	ds_read_b128 v[20:23], v193 offset:3072
	ds_read_b128 v[8:11], v194
	ds_read_b128 v[12:15], v194 offset:1024
	ds_read_b128 v[0:3], v194 offset:2048
	ds_read_b128 v[4:7], v194 offset:3072
	s_add_u32 s0, s36, 0xfff80080
	s_addc_u32 s1, s37, -1
	s_cmp_eq_u32 s65, 28
	s_cselect_b32 s41, s26, s1
	s_cselect_b32 s40, s27, s0
	s_cselect_b32 s39, s17, s64
	s_cselect_b32 s38, s31, s63
	s_add_i32 m0, s35, 0xc000
	ds_read_b128 v[180:183], v195
	ds_read_b128 v[184:187], v195 offset:1024
	ds_read_b128 v[210:213], v195 offset:2048
	ds_read_b128 v[214:217], v195 offset:3072
	ds_read_b128 v[218:221], v195 offset:4096
	ds_read_b128 v[222:225], v195 offset:5120
	ds_read_b128 v[226:229], v195 offset:6144
	global_load_lds_dwordx4 v172, s[36:37]
	s_add_i32 m0, s35, 0xe000
	ds_read_b128 v[230:233], v195 offset:7168
	global_load_lds_dwordx4 v174, s[36:37]
	s_waitcnt vmcnt(8) lgkmcnt(0)
	s_setprio 3
	s_barrier
	v_mfma_scale_f32_16x16x128_f8f6f4 v[152:155], v[24:31], v[180:187], v[152:155], v188, v188 op_sel_hi:[0,0,0]
	v_mfma_scale_f32_16x16x128_f8f6f4 v[148:151], v[16:23], v[180:187], v[148:151], v188, v188 op_sel_hi:[0,0,0]
	v_mfma_scale_f32_16x16x128_f8f6f4 v[140:143], v[24:31], v[210:217], v[140:143], v188, v188 op_sel_hi:[0,0,0]
	v_mfma_scale_f32_16x16x128_f8f6f4 v[132:135], v[16:23], v[210:217], v[132:135], v188, v188 op_sel_hi:[0,0,0]
	v_mfma_scale_f32_16x16x128_f8f6f4 v[124:127], v[24:31], v[218:225], v[124:127], v188, v188 op_sel_hi:[0,0,0]
	v_mfma_scale_f32_16x16x128_f8f6f4 v[120:123], v[16:23], v[218:225], v[120:123], v188, v188 op_sel_hi:[0,0,0]
	v_mfma_scale_f32_16x16x128_f8f6f4 v[108:111], v[24:31], v[226:233], v[108:111], v188, v188 op_sel_hi:[0,0,0]
	v_mfma_scale_f32_16x16x128_f8f6f4 v[100:103], v[16:23], v[226:233], v[100:103], v188, v188 op_sel_hi:[0,0,0]
	v_mfma_scale_f32_16x16x128_f8f6f4 v[156:159], v[8:15], v[180:187], v[156:159], v188, v188 op_sel_hi:[0,0,0]
	v_mfma_scale_f32_16x16x128_f8f6f4 v[144:147], v[0:7], v[180:187], v[144:147], v188, v188 op_sel_hi:[0,0,0]
	v_mfma_scale_f32_16x16x128_f8f6f4 v[136:139], v[8:15], v[210:217], v[136:139], v188, v188 op_sel_hi:[0,0,0]
	v_mfma_scale_f32_16x16x128_f8f6f4 v[128:131], v[0:7], v[210:217], v[128:131], v188, v188 op_sel_hi:[0,0,0]
	v_mfma_scale_f32_16x16x128_f8f6f4 v[116:119], v[8:15], v[218:225], v[116:119], v188, v188 op_sel_hi:[0,0,0]
	v_mfma_scale_f32_16x16x128_f8f6f4 v[112:115], v[0:7], v[218:225], v[112:115], v188, v188 op_sel_hi:[0,0,0]
	v_mfma_scale_f32_16x16x128_f8f6f4 v[104:107], v[8:15], v[226:233], v[104:107], v188, v188 op_sel_hi:[0,0,0]
	v_mfma_scale_f32_16x16x128_f8f6f4 v[96:99], v[0:7], v[226:233], v[96:99], v188, v188 op_sel_hi:[0,0,0]
	s_barrier
	s_setprio 0
	s_add_i32 m0, s56, s45
	ds_read_b128 v[210:213], v195 offset:16384
	ds_read_b128 v[214:217], v195 offset:17408
	ds_read_b128 v[218:221], v195 offset:18432
	ds_read_b128 v[222:225], v195 offset:19456
	ds_read_b128 v[226:229], v195 offset:20480
	global_load_lds_dwordx4 v164, s[38:39]
	s_add_i32 m0, m0, 0x2000
	s_add_u32 s0, s38, 0x80000
	s_addc_u32 s1, s39, 0
	s_add_i32 s66, s57, s45
	global_load_lds_dwordx4 v168, s[38:39]
	s_mov_b32 m0, s66
	s_nop 0
	global_load_lds_dwordx4 v164, s[0:1]
	s_add_i32 m0, s66, 0x2000
	ds_read_b128 v[238:241], v195 offset:23552
	global_load_lds_dwordx4 v168, s[0:1]
	s_mov_b32 m0, s35
	ds_read_b128 v[234:237], v195 offset:22528
	global_load_lds_dwordx4 v162, s[40:41]
	s_mov_b32 m0, s46
	ds_read_b128 v[230:233], v195 offset:21504
	global_load_lds_dwordx4 v166, s[40:41]
	s_waitcnt vmcnt(8) lgkmcnt(0)
	s_setprio 3
	s_barrier
	v_mfma_scale_f32_16x16x128_f8f6f4 v[92:95], v[24:31], v[210:217], v[92:95], v188, v188 op_sel_hi:[0,0,0]
	v_mfma_scale_f32_16x16x128_f8f6f4 v[88:91], v[16:23], v[210:217], v[88:91], v188, v188 op_sel_hi:[0,0,0]
	v_mfma_scale_f32_16x16x128_f8f6f4 v[76:79], v[24:31], v[218:225], v[76:79], v188, v188 op_sel_hi:[0,0,0]
	v_mfma_scale_f32_16x16x128_f8f6f4 v[68:71], v[16:23], v[218:225], v[68:71], v188, v188 op_sel_hi:[0,0,0]
	v_mfma_scale_f32_16x16x128_f8f6f4 v[60:63], v[24:31], v[226:233], v[60:63], v188, v188 op_sel_hi:[0,0,0]
	v_mfma_scale_f32_16x16x128_f8f6f4 v[56:59], v[16:23], v[226:233], v[56:59], v188, v188 op_sel_hi:[0,0,0]
	v_mfma_scale_f32_16x16x128_f8f6f4 v[44:47], v[24:31], v[234:241], v[44:47], v188, v188 op_sel_hi:[0,0,0]
	v_mfma_scale_f32_16x16x128_f8f6f4 v[40:43], v[16:23], v[234:241], v[40:43], v188, v188 op_sel_hi:[0,0,0]
	v_mfma_scale_f32_16x16x128_f8f6f4 v[84:87], v[8:15], v[210:217], v[84:87], v188, v188 op_sel_hi:[0,0,0]
	v_mfma_scale_f32_16x16x128_f8f6f4 v[80:83], v[0:7], v[210:217], v[80:83], v188, v188 op_sel_hi:[0,0,0]
	v_mfma_scale_f32_16x16x128_f8f6f4 v[72:75], v[8:15], v[218:225], v[72:75], v188, v188 op_sel_hi:[0,0,0]
	v_mfma_scale_f32_16x16x128_f8f6f4 v[64:67], v[0:7], v[218:225], v[64:67], v188, v188 op_sel_hi:[0,0,0]
	v_mfma_scale_f32_16x16x128_f8f6f4 v[52:55], v[8:15], v[226:233], v[52:55], v188, v188 op_sel_hi:[0,0,0]
	v_mfma_scale_f32_16x16x128_f8f6f4 v[48:51], v[0:7], v[226:233], v[48:51], v188, v188 op_sel_hi:[0,0,0]
	v_mfma_scale_f32_16x16x128_f8f6f4 v[36:39], v[8:15], v[234:241], v[36:39], v188, v188 op_sel_hi:[0,0,0]
	v_mfma_scale_f32_16x16x128_f8f6f4 v[32:35], v[0:7], v[234:241], v[32:35], v188, v188 op_sel_hi:[0,0,0]
	s_barrier
	s_setprio 0
	s_add_i32 s66, 0, 0x18000
	s_add_i32 s67, 0, 0x1c000
	ds_read_b128 v[0:3], v198
	ds_read_b128 v[4:7], v198 offset:1024
	ds_read_b128 v[8:11], v198 offset:2048
	ds_read_b128 v[12:15], v198 offset:3072
	ds_read_b128 v[16:19], v199
	ds_read_b128 v[20:23], v199 offset:1024
	ds_read_b128 v[24:27], v199 offset:2048
	ds_read_b128 v[28:31], v199 offset:3072
	s_add_u32 s0, s40, 0x80000
	s_addc_u32 s1, s41, 0
	s_mov_b32 m0, s47
	ds_read_b128 v[210:213], v195 offset:32768
	ds_read_b128 v[214:217], v195 offset:33792
	ds_read_b128 v[218:221], v195 offset:34816
	ds_read_b128 v[222:225], v195 offset:35840
	ds_read_b128 v[226:229], v195 offset:36864
	ds_read_b128 v[230:233], v195 offset:37888
	ds_read_b128 v[234:237], v195 offset:38912
	global_load_lds_dwordx4 v162, s[0:1]
	s_mov_b32 m0, s48
	ds_read_b128 v[238:241], v195 offset:39936
	global_load_lds_dwordx4 v166, s[0:1]
	s_waitcnt vmcnt(8) lgkmcnt(0)
	s_setprio 3
	s_barrier
	v_mfma_scale_f32_16x16x128_f8f6f4 v[152:155], v[0:7], v[210:217], v[152:155], v188, v188 op_sel_hi:[0,0,0]
	v_mfma_scale_f32_16x16x128_f8f6f4 v[148:151], v[8:15], v[210:217], v[148:151], v188, v188 op_sel_hi:[0,0,0]
	v_mfma_scale_f32_16x16x128_f8f6f4 v[140:143], v[0:7], v[218:225], v[140:143], v188, v188 op_sel_hi:[0,0,0]
	v_mfma_scale_f32_16x16x128_f8f6f4 v[132:135], v[8:15], v[218:225], v[132:135], v188, v188 op_sel_hi:[0,0,0]
	v_mfma_scale_f32_16x16x128_f8f6f4 v[124:127], v[0:7], v[226:233], v[124:127], v188, v188 op_sel_hi:[0,0,0]
	v_mfma_scale_f32_16x16x128_f8f6f4 v[120:123], v[8:15], v[226:233], v[120:123], v188, v188 op_sel_hi:[0,0,0]
	v_mfma_scale_f32_16x16x128_f8f6f4 v[108:111], v[0:7], v[234:241], v[108:111], v188, v188 op_sel_hi:[0,0,0]
	v_mfma_scale_f32_16x16x128_f8f6f4 v[100:103], v[8:15], v[234:241], v[100:103], v188, v188 op_sel_hi:[0,0,0]
	v_mfma_scale_f32_16x16x128_f8f6f4 v[156:159], v[16:23], v[210:217], v[156:159], v188, v188 op_sel_hi:[0,0,0]
	v_mfma_scale_f32_16x16x128_f8f6f4 v[144:147], v[24:31], v[210:217], v[144:147], v188, v188 op_sel_hi:[0,0,0]
	v_mfma_scale_f32_16x16x128_f8f6f4 v[136:139], v[16:23], v[218:225], v[136:139], v188, v188 op_sel_hi:[0,0,0]
	v_mfma_scale_f32_16x16x128_f8f6f4 v[128:131], v[24:31], v[218:225], v[128:131], v188, v188 op_sel_hi:[0,0,0]
	v_mfma_scale_f32_16x16x128_f8f6f4 v[116:119], v[16:23], v[226:233], v[116:119], v188, v188 op_sel_hi:[0,0,0]
	v_mfma_scale_f32_16x16x128_f8f6f4 v[112:115], v[24:31], v[226:233], v[112:115], v188, v188 op_sel_hi:[0,0,0]
	v_mfma_scale_f32_16x16x128_f8f6f4 v[104:107], v[16:23], v[234:241], v[104:107], v188, v188 op_sel_hi:[0,0,0]
	v_mfma_scale_f32_16x16x128_f8f6f4 v[96:99], v[24:31], v[234:241], v[96:99], v188, v188 op_sel_hi:[0,0,0]
	s_barrier
	s_setprio 0
	s_add_u32 s100, s38, 0x80
	s_addc_u32 s101, s39, 0
	s_add_i32 m0, s66, s45
	ds_read_b128 v[210:213], v195 offset:49152
	ds_read_b128 v[214:217], v195 offset:50176
	ds_read_b128 v[218:221], v195 offset:51200
	ds_read_b128 v[222:225], v195 offset:52224
	global_load_lds_dwordx4 v164, s[100:101]
	s_add_i32 m0, m0, 0x2000
	s_add_u32 s0, s38, 0x80080
	s_addc_u32 s1, s39, 0
	s_add_i32 s38, s67, s45
	global_load_lds_dwordx4 v168, s[100:101]
	s_mov_b32 m0, s38
	ds_read_b128 v[238:241], v195 offset:56320
	global_load_lds_dwordx4 v164, s[0:1]
	s_add_i32 m0, s38, 0x2000
	ds_read_b128 v[234:237], v195 offset:55296
	global_load_lds_dwordx4 v168, s[0:1]
	s_add_u32 s100, s40, 0x80
	s_addc_u32 s101, s41, 0
	s_mov_b32 m0, s51
	ds_read_b128 v[230:233], v195 offset:54272
	global_load_lds_dwordx4 v162, s[100:101]
	s_mov_b32 m0, s52
	ds_read_b128 v[226:229], v195 offset:53248
	global_load_lds_dwordx4 v166, s[100:101]
	s_waitcnt vmcnt(8) lgkmcnt(0)
	s_setprio 3
	s_barrier
	v_mfma_scale_f32_16x16x128_f8f6f4 v[92:95], v[0:7], v[210:217], v[92:95], v188, v188 op_sel_hi:[0,0,0]
	v_mfma_scale_f32_16x16x128_f8f6f4 v[88:91], v[8:15], v[210:217], v[88:91], v188, v188 op_sel_hi:[0,0,0]
	v_mfma_scale_f32_16x16x128_f8f6f4 v[76:79], v[0:7], v[218:225], v[76:79], v188, v188 op_sel_hi:[0,0,0]
	v_mfma_scale_f32_16x16x128_f8f6f4 v[68:71], v[8:15], v[218:225], v[68:71], v188, v188 op_sel_hi:[0,0,0]
	v_mfma_scale_f32_16x16x128_f8f6f4 v[60:63], v[0:7], v[226:233], v[60:63], v188, v188 op_sel_hi:[0,0,0]
	v_mfma_scale_f32_16x16x128_f8f6f4 v[56:59], v[8:15], v[226:233], v[56:59], v188, v188 op_sel_hi:[0,0,0]
	v_mfma_scale_f32_16x16x128_f8f6f4 v[44:47], v[0:7], v[234:241], v[44:47], v188, v188 op_sel_hi:[0,0,0]
	v_mfma_scale_f32_16x16x128_f8f6f4 v[40:43], v[8:15], v[234:241], v[40:43], v188, v188 op_sel_hi:[0,0,0]
	v_mfma_scale_f32_16x16x128_f8f6f4 v[84:87], v[16:23], v[210:217], v[84:87], v188, v188 op_sel_hi:[0,0,0]
	v_mfma_scale_f32_16x16x128_f8f6f4 v[80:83], v[24:31], v[210:217], v[80:83], v188, v188 op_sel_hi:[0,0,0]
	v_mfma_scale_f32_16x16x128_f8f6f4 v[72:75], v[16:23], v[218:225], v[72:75], v188, v188 op_sel_hi:[0,0,0]
	v_mfma_scale_f32_16x16x128_f8f6f4 v[64:67], v[24:31], v[218:225], v[64:67], v188, v188 op_sel_hi:[0,0,0]
	v_mfma_scale_f32_16x16x128_f8f6f4 v[52:55], v[16:23], v[226:233], v[52:55], v188, v188 op_sel_hi:[0,0,0]
	v_mfma_scale_f32_16x16x128_f8f6f4 v[48:51], v[24:31], v[226:233], v[48:51], v188, v188 op_sel_hi:[0,0,0]
	v_mfma_scale_f32_16x16x128_f8f6f4 v[36:39], v[16:23], v[234:241], v[36:39], v188, v188 op_sel_hi:[0,0,0]
	v_mfma_scale_f32_16x16x128_f8f6f4 v[32:35], v[24:31], v[234:241], v[32:35], v188, v188 op_sel_hi:[0,0,0]
	s_barrier
	s_setprio 0
	s_add_u32 s36, s36, 0x100
	s_addc_u32 s37, s37, 0
	s_add_i32 s65, s65, 2
	s_add_u32 s63, s63, 0x100
	s_addc_u32 s64, s64, 0
	s_cmp_gt_u32 s65, 29
	s_cbranch_scc0 .LBB0_1833
	s_and_b64 vcc, exec, s[14:15]
	s_cbranch_vccz .LBB0_1836
	s_barrier

.LBB0_1974:
	v_add_u32_e32 v0, s65, v182
	v_add_u32_e32 v4, s66, v182
	ds_read_b128 v[24:27], v0
	ds_read_b128 v[28:31], v0 offset:1024
	ds_read_b128 v[16:19], v0 offset:2048
	ds_read_b128 v[20:23], v0 offset:3072
	ds_read_b128 v[8:11], v4
	ds_read_b128 v[12:15], v4 offset:1024
	ds_read_b128 v[0:3], v4 offset:2048
	ds_read_b128 v[4:7], v4 offset:3072
	s_add_i32 s35, s35, 2
	s_lshr_b32 s0, s35, 5
	s_mul_hi_u32 s1, s0, 0x4100000
	s_mul_i32 s0, s0, 0x4100000
	s_add_u32 s0, s46, s0
	s_addc_u32 s1, s47, s1
	s_and_b32 s37, s37, 0xf00
	s_add_u32 s0, s0, s37
	s_addc_u32 s1, s1, 0
	s_add_u32 s0, s0, 0x80080
	s_addc_u32 s1, s1, 0
	s_add_i32 m0, s43, 0xc000
	ds_read_b128 v[172:175], v184
	ds_read_b128 v[176:179], v184 offset:1024
	ds_read_b128 v[186:189], v184 offset:2048
	ds_read_b128 v[190:193], v184 offset:3072
	ds_read_b128 v[194:197], v184 offset:4096
	ds_read_b128 v[198:201], v184 offset:5120
	ds_read_b128 v[210:213], v184 offset:6144
	global_load_lds_dwordx4 v160, s[0:1]
	s_add_i32 m0, s43, 0xe000
	ds_read_b128 v[214:217], v184 offset:7168
	global_load_lds_dwordx4 v164, s[0:1]
	s_waitcnt vmcnt(8) lgkmcnt(0)
	s_setprio 3
	s_barrier
	v_mfma_scale_f32_16x16x128_f8f6f4 v[156:159], v[24:31], v[172:179], v[156:159], v180, v180 op_sel_hi:[0,0,0]
	v_mfma_scale_f32_16x16x128_f8f6f4 v[152:155], v[16:23], v[172:179], v[152:155], v180, v180 op_sel_hi:[0,0,0]
	v_mfma_scale_f32_16x16x128_f8f6f4 v[144:147], v[24:31], v[186:193], v[144:147], v180, v180 op_sel_hi:[0,0,0]
	v_mfma_scale_f32_16x16x128_f8f6f4 v[136:139], v[16:23], v[186:193], v[136:139], v180, v180 op_sel_hi:[0,0,0]
	v_mfma_scale_f32_16x16x128_f8f6f4 v[128:131], v[24:31], v[194:201], v[128:131], v180, v180 op_sel_hi:[0,0,0]
	v_mfma_scale_f32_16x16x128_f8f6f4 v[120:123], v[16:23], v[194:201], v[120:123], v180, v180 op_sel_hi:[0,0,0]
	v_mfma_scale_f32_16x16x128_f8f6f4 v[112:115], v[24:31], v[210:217], v[112:115], v180, v180 op_sel_hi:[0,0,0]
	v_mfma_scale_f32_16x16x128_f8f6f4 v[104:107], v[16:23], v[210:217], v[104:107], v180, v180 op_sel_hi:[0,0,0]
	v_mfma_scale_f32_16x16x128_f8f6f4 v[148:151], v[8:15], v[172:179], v[148:151], v180, v180 op_sel_hi:[0,0,0]
	v_mfma_scale_f32_16x16x128_f8f6f4 v[140:143], v[0:7], v[172:179], v[140:143], v180, v180 op_sel_hi:[0,0,0]
	v_mfma_scale_f32_16x16x128_f8f6f4 v[132:135], v[8:15], v[186:193], v[132:135], v180, v180 op_sel_hi:[0,0,0]
	v_mfma_scale_f32_16x16x128_f8f6f4 v[124:127], v[0:7], v[186:193], v[124:127], v180, v180 op_sel_hi:[0,0,0]
	v_mfma_scale_f32_16x16x128_f8f6f4 v[116:119], v[8:15], v[194:201], v[116:119], v180, v180 op_sel_hi:[0,0,0]
	v_mfma_scale_f32_16x16x128_f8f6f4 v[108:111], v[0:7], v[194:201], v[108:111], v180, v180 op_sel_hi:[0,0,0]
	v_mfma_scale_f32_16x16x128_f8f6f4 v[100:103], v[8:15], v[210:217], v[100:103], v180, v180 op_sel_hi:[0,0,0]
	v_mfma_scale_f32_16x16x128_f8f6f4 v[96:99], v[0:7], v[210:217], v[96:99], v180, v180 op_sel_hi:[0,0,0]
	s_barrier
	s_setprio 0
	s_add_i32 m0, s65, s58
	ds_read_b128 v[186:189], v184 offset:16384
	ds_read_b128 v[190:193], v184 offset:17408
	ds_read_b128 v[194:197], v184 offset:18432
	ds_read_b128 v[198:201], v184 offset:19456
	ds_read_b128 v[210:213], v184 offset:20480
	global_load_lds_dwordx4 v162, s[52:53]
	s_add_i32 m0, m0, 0x2000
	s_add_u32 s0, s52, 0x80000
	s_addc_u32 s1, s53, 0
	s_add_i32 s37, s66, s58
	global_load_lds_dwordx4 v166, s[52:53]
	s_mov_b32 m0, s37
	s_nop 0
	global_load_lds_dwordx4 v162, s[0:1]
	s_add_i32 m0, s37, 0x2000
	ds_read_b128 v[222:225], v184 offset:23552
	global_load_lds_dwordx4 v166, s[0:1]
	s_mov_b32 m0, s43
	ds_read_b128 v[218:221], v184 offset:22528
	global_load_lds_dwordx4 v160, s[54:55]
	s_mov_b32 m0, s59
	ds_read_b128 v[214:217], v184 offset:21504
	global_load_lds_dwordx4 v164, s[54:55]
	s_waitcnt vmcnt(8) lgkmcnt(0)
	s_setprio 3
	s_barrier
	v_mfma_scale_f32_16x16x128_f8f6f4 v[92:95], v[24:31], v[186:193], v[92:95], v180, v180 op_sel_hi:[0,0,0]
	v_mfma_scale_f32_16x16x128_f8f6f4 v[88:91], v[16:23], v[186:193], v[88:91], v180, v180 op_sel_hi:[0,0,0]
	v_mfma_scale_f32_16x16x128_f8f6f4 v[80:83], v[24:31], v[194:201], v[80:83], v180, v180 op_sel_hi:[0,0,0]
	v_mfma_scale_f32_16x16x128_f8f6f4 v[72:75], v[16:23], v[194:201], v[72:75], v180, v180 op_sel_hi:[0,0,0]
	v_mfma_scale_f32_16x16x128_f8f6f4 v[64:67], v[24:31], v[210:217], v[64:67], v180, v180 op_sel_hi:[0,0,0]
	v_mfma_scale_f32_16x16x128_f8f6f4 v[56:59], v[16:23], v[210:217], v[56:59], v180, v180 op_sel_hi:[0,0,0]
	v_mfma_scale_f32_16x16x128_f8f6f4 v[48:51], v[24:31], v[218:225], v[48:51], v180, v180 op_sel_hi:[0,0,0]
	v_mfma_scale_f32_16x16x128_f8f6f4 v[40:43], v[16:23], v[218:225], v[40:43], v180, v180 op_sel_hi:[0,0,0]
	v_mfma_scale_f32_16x16x128_f8f6f4 v[84:87], v[8:15], v[186:193], v[84:87], v180, v180 op_sel_hi:[0,0,0]
	v_mfma_scale_f32_16x16x128_f8f6f4 v[76:79], v[0:7], v[186:193], v[76:79], v180, v180 op_sel_hi:[0,0,0]
	v_mfma_scale_f32_16x16x128_f8f6f4 v[68:71], v[8:15], v[194:201], v[68:71], v180, v180 op_sel_hi:[0,0,0]
	v_mfma_scale_f32_16x16x128_f8f6f4 v[60:63], v[0:7], v[194:201], v[60:63], v180, v180 op_sel_hi:[0,0,0]
	v_mfma_scale_f32_16x16x128_f8f6f4 v[52:55], v[8:15], v[210:217], v[52:55], v180, v180 op_sel_hi:[0,0,0]
	v_mfma_scale_f32_16x16x128_f8f6f4 v[44:47], v[0:7], v[210:217], v[44:47], v180, v180 op_sel_hi:[0,0,0]
	v_mfma_scale_f32_16x16x128_f8f6f4 v[36:39], v[8:15], v[218:225], v[36:39], v180, v180 op_sel_hi:[0,0,0]
	v_mfma_scale_f32_16x16x128_f8f6f4 v[32:35], v[0:7], v[218:225], v[32:35], v180, v180 op_sel_hi:[0,0,0]
	s_barrier
	s_setprio 0
	s_add_i32 s37, 0, 0x18000
	s_add_i32 s56, 0, 0x1c000
	v_add_u32_e32 v12, s37, v182
	v_add_u32_e32 v28, s56, v182
	ds_read_b128 v[0:3], v12
	ds_read_b128 v[4:7], v12 offset:1024
	ds_read_b128 v[8:11], v12 offset:2048
	ds_read_b128 v[12:15], v12 offset:3072
	ds_read_b128 v[16:19], v28
	ds_read_b128 v[20:23], v28 offset:1024
	ds_read_b128 v[24:27], v28 offset:2048
	ds_read_b128 v[28:31], v28 offset:3072
	s_add_u32 s0, s54, 0x80000
	s_addc_u32 s1, s55, 0
	s_mov_b32 m0, s60
	ds_read_b128 v[186:189], v184 offset:32768
	ds_read_b128 v[190:193], v184 offset:33792
	ds_read_b128 v[194:197], v184 offset:34816
	ds_read_b128 v[198:201], v184 offset:35840
	ds_read_b128 v[210:213], v184 offset:36864
	ds_read_b128 v[214:217], v184 offset:37888
	ds_read_b128 v[218:221], v184 offset:38912
	global_load_lds_dwordx4 v160, s[0:1]
	s_mov_b32 m0, s61
	ds_read_b128 v[222:225], v184 offset:39936
	global_load_lds_dwordx4 v164, s[0:1]
	s_waitcnt vmcnt(8) lgkmcnt(0)
	s_setprio 3
	s_barrier
	v_mfma_scale_f32_16x16x128_f8f6f4 v[156:159], v[0:7], v[186:193], v[156:159], v180, v180 op_sel_hi:[0,0,0]
	v_mfma_scale_f32_16x16x128_f8f6f4 v[152:155], v[8:15], v[186:193], v[152:155], v180, v180 op_sel_hi:[0,0,0]
	v_mfma_scale_f32_16x16x128_f8f6f4 v[144:147], v[0:7], v[194:201], v[144:147], v180, v180 op_sel_hi:[0,0,0]
	v_mfma_scale_f32_16x16x128_f8f6f4 v[136:139], v[8:15], v[194:201], v[136:139], v180, v180 op_sel_hi:[0,0,0]
	v_mfma_scale_f32_16x16x128_f8f6f4 v[128:131], v[0:7], v[210:217], v[128:131], v180, v180 op_sel_hi:[0,0,0]
	v_mfma_scale_f32_16x16x128_f8f6f4 v[120:123], v[8:15], v[210:217], v[120:123], v180, v180 op_sel_hi:[0,0,0]
	v_mfma_scale_f32_16x16x128_f8f6f4 v[112:115], v[0:7], v[218:225], v[112:115], v180, v180 op_sel_hi:[0,0,0]
	v_mfma_scale_f32_16x16x128_f8f6f4 v[104:107], v[8:15], v[218:225], v[104:107], v180, v180 op_sel_hi:[0,0,0]
	v_mfma_scale_f32_16x16x128_f8f6f4 v[148:151], v[16:23], v[186:193], v[148:151], v180, v180 op_sel_hi:[0,0,0]
	v_mfma_scale_f32_16x16x128_f8f6f4 v[140:143], v[24:31], v[186:193], v[140:143], v180, v180 op_sel_hi:[0,0,0]
	v_mfma_scale_f32_16x16x128_f8f6f4 v[132:135], v[16:23], v[194:201], v[132:135], v180, v180 op_sel_hi:[0,0,0]
	v_mfma_scale_f32_16x16x128_f8f6f4 v[124:127], v[24:31], v[194:201], v[124:127], v180, v180 op_sel_hi:[0,0,0]
	v_mfma_scale_f32_16x16x128_f8f6f4 v[116:119], v[16:23], v[210:217], v[116:119], v180, v180 op_sel_hi:[0,0,0]
	v_mfma_scale_f32_16x16x128_f8f6f4 v[108:111], v[24:31], v[210:217], v[108:111], v180, v180 op_sel_hi:[0,0,0]
	v_mfma_scale_f32_16x16x128_f8f6f4 v[100:103], v[16:23], v[218:225], v[100:103], v180, v180 op_sel_hi:[0,0,0]
	v_mfma_scale_f32_16x16x128_f8f6f4 v[96:99], v[24:31], v[218:225], v[96:99], v180, v180 op_sel_hi:[0,0,0]
	s_barrier
	s_setprio 0
	s_add_u32 s100, s52, 0x80
	s_addc_u32 s101, s53, 0
	s_add_i32 m0, s37, s58
	ds_read_b128 v[186:189], v184 offset:49152
	ds_read_b128 v[190:193], v184 offset:50176
	ds_read_b128 v[194:197], v184 offset:51200
	ds_read_b128 v[198:201], v184 offset:52224
	global_load_lds_dwordx4 v162, s[100:101]
	s_add_i32 m0, m0, 0x2000
	s_add_u32 s0, s52, 0x80080
	s_addc_u32 s1, s53, 0
	s_add_i32 s37, s56, s58
	global_load_lds_dwordx4 v166, s[100:101]
	s_mov_b32 m0, s37
	ds_read_b128 v[222:225], v184 offset:56320
	global_load_lds_dwordx4 v162, s[0:1]
	s_add_i32 m0, s37, 0x2000
	ds_read_b128 v[218:221], v184 offset:55296
	global_load_lds_dwordx4 v166, s[0:1]
	s_add_u32 s100, s54, 0x80
	s_addc_u32 s101, s55, 0
	s_mov_b32 m0, s62
	ds_read_b128 v[214:217], v184 offset:54272
	global_load_lds_dwordx4 v160, s[100:101]
	s_mov_b32 m0, s63
	ds_read_b128 v[210:213], v184 offset:53248
	global_load_lds_dwordx4 v164, s[100:101]
	s_waitcnt vmcnt(8) lgkmcnt(0)
	s_setprio 3
	s_barrier
	v_mfma_scale_f32_16x16x128_f8f6f4 v[92:95], v[0:7], v[186:193], v[92:95], v180, v180 op_sel_hi:[0,0,0]
	v_mfma_scale_f32_16x16x128_f8f6f4 v[88:91], v[8:15], v[186:193], v[88:91], v180, v180 op_sel_hi:[0,0,0]
	v_mfma_scale_f32_16x16x128_f8f6f4 v[80:83], v[0:7], v[194:201], v[80:83], v180, v180 op_sel_hi:[0,0,0]
	v_mfma_scale_f32_16x16x128_f8f6f4 v[72:75], v[8:15], v[194:201], v[72:75], v180, v180 op_sel_hi:[0,0,0]
	v_mfma_scale_f32_16x16x128_f8f6f4 v[64:67], v[0:7], v[210:217], v[64:67], v180, v180 op_sel_hi:[0,0,0]
	v_mfma_scale_f32_16x16x128_f8f6f4 v[56:59], v[8:15], v[210:217], v[56:59], v180, v180 op_sel_hi:[0,0,0]
	v_mfma_scale_f32_16x16x128_f8f6f4 v[48:51], v[0:7], v[218:225], v[48:51], v180, v180 op_sel_hi:[0,0,0]
	v_mfma_scale_f32_16x16x128_f8f6f4 v[40:43], v[8:15], v[218:225], v[40:43], v180, v180 op_sel_hi:[0,0,0]
	v_mfma_scale_f32_16x16x128_f8f6f4 v[84:87], v[16:23], v[186:193], v[84:87], v180, v180 op_sel_hi:[0,0,0]
	v_mfma_scale_f32_16x16x128_f8f6f4 v[76:79], v[24:31], v[186:193], v[76:79], v180, v180 op_sel_hi:[0,0,0]
	v_mfma_scale_f32_16x16x128_f8f6f4 v[68:71], v[16:23], v[194:201], v[68:71], v180, v180 op_sel_hi:[0,0,0]
	v_mfma_scale_f32_16x16x128_f8f6f4 v[60:63], v[24:31], v[194:201], v[60:63], v180, v180 op_sel_hi:[0,0,0]
	v_mfma_scale_f32_16x16x128_f8f6f4 v[52:55], v[16:23], v[210:217], v[52:55], v180, v180 op_sel_hi:[0,0,0]
	v_mfma_scale_f32_16x16x128_f8f6f4 v[44:47], v[24:31], v[210:217], v[44:47], v180, v180 op_sel_hi:[0,0,0]
	v_mfma_scale_f32_16x16x128_f8f6f4 v[36:39], v[16:23], v[218:225], v[36:39], v180, v180 op_sel_hi:[0,0,0]
	v_mfma_scale_f32_16x16x128_f8f6f4 v[32:35], v[24:31], v[218:225], v[32:35], v180, v180 op_sel_hi:[0,0,0]
	s_barrier
	s_setprio 0
	s_cmpk_gt_u32 s35, 0x53
	s_mov_b32 s37, s6
	s_cbranch_scc1 .LBB0_1981
